# also non-temporal: the P2-tail weight-copy streams (f32 weight reads, bf16 copy stores) and the gMLP VG tile loads, so they do not displace GA/GB/AG that the branch-merge phase reads next
# speedup vs baseline: 1.0170x; 1.0053x over previous
.LBB0_685:
	s_lshl_b32 s28, s15, 1
	s_lshl_b32 s29, s22, 1
	v_or_b32_e32 v47, s29, v10
	s_add_i32 s30, s28, 4
	s_add_i32 s31, s29, 4
	s_add_i32 s34, s29, 8
	v_add_u32_e32 v12, s13, v47
	v_or_b32_e32 v48, s30, v1
	v_or_b32_e32 v49, s31, v10
	v_mov_b32_e32 v7, v13
	v_or_b32_e32 v46, s28, v1
	s_add_i32 s36, s29, 12
	v_or_b32_e32 v51, s34, v10
	v_lshlrev_b64 v[40:41], 12, v[12:13]
	v_add_u32_e32 v6, s0, v48
	v_add_u32_e32 v12, s13, v49
	v_mov_b32_e32 v5, v13
	s_add_i32 s33, s28, 8
	s_add_i32 s35, s28, 12
	s_add_i32 s38, s29, 16
	v_add_u32_e32 v4, s0, v46
	v_or_b32_e32 v53, s36, v10
	v_lshlrev_b64 v[6:7], 12, v[6:7]
	v_lshlrev_b64 v[42:43], 12, v[12:13]
	v_add_u32_e32 v12, s13, v51
	s_add_i32 s40, s29, 20
	v_or_b32_e32 v50, s33, v1
	v_or_b32_e32 v52, s35, v1
	v_or_b32_e32 v55, s38, v10
	v_lshlrev_b64 v[4:5], 12, v[4:5]
	v_lshl_add_u64 v[40:41], v[2:3], 0, v[40:41]
	v_lshl_add_u64 v[6:7], v[2:3], 0, v[6:7]
	v_lshlrev_b64 v[44:45], 12, v[12:13]
	v_add_u32_e32 v12, s13, v53
	v_mov_b32_e32 v9, v13
	v_mov_b32_e32 v31, v13
	s_add_i32 s37, s28, 16
	s_add_i32 s39, s28, 20
	s_add_i32 s42, s29, 24
	v_or_b32_e32 v57, s40, v10
	v_add_u32_e32 v8, s0, v50
	v_add_u32_e32 v30, s0, v52
	v_lshl_add_u64 v[4:5], v[2:3], 0, v[4:5]
	v_lshl_add_u64 v[42:43], v[2:3], 0, v[42:43]
	global_load_dword v62, v[40:41], off nt
	global_load_dword v63, v[4:5], off nt
	global_load_dword v64, v[42:43], off nt
	global_load_dword v65, v[6:7], off nt
	v_lshlrev_b64 v[6:7], 12, v[12:13]
	v_add_u32_e32 v12, s13, v55
	s_add_i32 s41, s28, 24
	s_add_i32 s28, s28, 28
	s_add_i32 s29, s29, 28
	v_or_b32_e32 v54, s37, v1
	v_or_b32_e32 v56, s39, v1
	v_or_b32_e32 v59, s42, v10
	v_lshlrev_b64 v[8:9], 12, v[8:9]
	v_lshlrev_b64 v[30:31], 12, v[30:31]
	v_lshl_add_u64 v[4:5], v[2:3], 0, v[44:45]
	v_lshl_add_u64 v[6:7], v[2:3], 0, v[6:7]
	v_lshlrev_b64 v[40:41], 12, v[12:13]
	v_add_u32_e32 v12, s13, v57
	v_mov_b32_e32 v33, v13
	v_mov_b32_e32 v35, v13
	v_or_b32_e32 v58, s41, v1
	v_or_b32_e32 v60, s28, v1
	v_or_b32_e32 v61, s29, v10
	v_add_u32_e32 v32, s0, v54
	v_add_u32_e32 v34, s0, v56
	v_lshl_add_u64 v[8:9], v[2:3], 0, v[8:9]
	v_lshl_add_u64 v[30:31], v[2:3], 0, v[30:31]
	global_load_dword v66, v[4:5], off nt
	global_load_dword v67, v[8:9], off nt
	global_load_dword v68, v[6:7], off nt
	global_load_dword v69, v[30:31], off nt
	v_lshlrev_b64 v[6:7], 12, v[12:13]
	v_add_u32_e32 v12, s13, v59
	v_mov_b32_e32 v37, v13
	v_mov_b32_e32 v39, v13
	v_add_u32_e32 v36, s0, v58
	v_add_u32_e32 v38, s0, v60
	v_lshlrev_b64 v[32:33], 12, v[32:33]
	v_lshlrev_b64 v[34:35], 12, v[34:35]
	v_lshl_add_u64 v[4:5], v[2:3], 0, v[40:41]
	v_lshl_add_u64 v[6:7], v[2:3], 0, v[6:7]
	v_lshlrev_b64 v[8:9], 12, v[12:13]
	v_add_u32_e32 v12, s13, v61
	v_lshlrev_b64 v[36:37], 12, v[36:37]
	v_lshlrev_b64 v[38:39], 12, v[38:39]
	v_lshl_add_u64 v[32:33], v[2:3], 0, v[32:33]
	v_lshl_add_u64 v[34:35], v[2:3], 0, v[34:35]
	global_load_dword v70, v[4:5], off nt
	global_load_dword v71, v[32:33], off nt
	global_load_dword v72, v[6:7], off nt
	global_load_dword v73, v[34:35], off nt
	v_lshl_add_u64 v[4:5], v[2:3], 0, v[8:9]
	v_lshlrev_b64 v[6:7], 12, v[12:13]
	v_lshl_add_u64 v[36:37], v[2:3], 0, v[36:37]
	v_lshl_add_u64 v[38:39], v[2:3], 0, v[38:39]
	v_lshl_add_u64 v[6:7], v[2:3], 0, v[6:7]
	global_load_dword v12, v[4:5], off nt
	global_load_dword v79, v[36:37], off nt
	global_load_dword v80, v[6:7], off nt
	global_load_dword v81, v[38:39], off nt
	s_add_i32 s22, s22, 16
	s_add_i32 s15, s15, 16
	s_add_i32 s23, s23, -16
	v_mad_u64_u32 v[4:5], s[28:29], v47, s3, v[16:17]
	s_cmp_lg_u32 s23, 0
	v_mad_u64_u32 v[6:7], s[28:29], v46, s3, v[16:17]
	v_mad_u64_u32 v[8:9], s[28:29], v49, s3, v[16:17]
	v_mad_u64_u32 v[30:31], s[28:29], v48, s3, v[16:17]
	v_mad_u64_u32 v[32:33], s[28:29], v51, s3, v[16:17]
	v_mad_u64_u32 v[34:35], s[28:29], v50, s3, v[16:17]
	v_mad_u64_u32 v[36:37], s[28:29], v53, s3, v[16:17]
	v_mad_u64_u32 v[38:39], s[28:29], v52, s3, v[16:17]
	v_mad_u64_u32 v[40:41], s[28:29], v55, s3, v[16:17]
	v_mad_u64_u32 v[42:43], s[28:29], v54, s3, v[16:17]
	v_mad_u64_u32 v[44:45], s[28:29], v57, s3, v[16:17]
	v_mad_u64_u32 v[46:47], s[28:29], v56, s3, v[16:17]
	v_mad_u64_u32 v[48:49], s[28:29], v59, s3, v[16:17]
	v_mad_u64_u32 v[50:51], s[28:29], v58, s3, v[16:17]
	v_mad_u64_u32 v[52:53], s[28:29], v61, s3, v[16:17]
	v_mad_u64_u32 v[54:55], s[28:29], v60, s3, v[16:17]
	s_waitcnt vmcnt(15)
	ds_write_b32 v4, v62
	s_waitcnt vmcnt(14)
	ds_write_b32 v6, v63
	s_waitcnt vmcnt(13)
	ds_write_b32 v8, v64
	s_waitcnt vmcnt(12)
	ds_write_b32 v30, v65
	s_waitcnt vmcnt(11)
	ds_write_b32 v32, v66
	s_waitcnt vmcnt(10)
	ds_write_b32 v34, v67
	s_waitcnt vmcnt(9)
	ds_write_b32 v36, v68
	s_waitcnt vmcnt(8)
	ds_write_b32 v38, v69
	s_waitcnt vmcnt(7)
	ds_write_b32 v40, v70
	s_waitcnt vmcnt(6)
	ds_write_b32 v42, v71
	s_waitcnt vmcnt(5)
	ds_write_b32 v44, v72
	s_waitcnt vmcnt(4)
	ds_write_b32 v46, v73
	s_waitcnt vmcnt(3)
	ds_write_b32 v48, v12
	s_waitcnt vmcnt(2)
	ds_write_b32 v50, v79
	s_waitcnt vmcnt(1)
	ds_write_b32 v52, v80
	s_waitcnt vmcnt(0)
	ds_write_b32 v54, v81
	s_cbranch_scc1 .LBB0_685
	s_waitcnt lgkmcnt(0)
	ds_read2_b32 v[6:7], v17 offset1:8
	ds_read2_b32 v[30:31], v17 offset0:33 offset1:41
	ds_read2_b32 v[32:33], v17 offset0:66 offset1:74
	ds_read2_b32 v[34:35], v17 offset0:99 offset1:107
	ds_read2_b32 v[36:37], v17 offset0:132 offset1:140
	ds_read2_b32 v[38:39], v17 offset0:165 offset1:173
	s_waitcnt lgkmcnt(5)
	v_bfe_u32 v2, v6, 16, 1
	v_add3_u32 v2, v6, v2, s17
	s_waitcnt lgkmcnt(4)
	v_bfe_u32 v3, v30, 16, 1
	v_lshrrev_b32_e32 v2, 16, v2
	v_add3_u32 v3, v30, v3, s17
	v_and_or_b32 v2, v3, s18, v2
	s_waitcnt lgkmcnt(3)
	v_bfe_u32 v3, v32, 16, 1
	v_add3_u32 v3, v32, v3, s17
	s_waitcnt lgkmcnt(2)
	v_bfe_u32 v4, v34, 16, 1
	ds_read2_b32 v[40:41], v17 offset0:198 offset1:206
	v_lshrrev_b32_e32 v3, 16, v3
	v_add3_u32 v4, v34, v4, s17
	ds_read2_b32 v[42:43], v17 offset0:231 offset1:239
	v_and_or_b32 v3, v4, s18, v3
	s_waitcnt lgkmcnt(3)
	v_bfe_u32 v4, v36, 16, 1
	v_add3_u32 v4, v36, v4, s17
	s_waitcnt lgkmcnt(2)
	v_bfe_u32 v5, v38, 16, 1
	v_lshrrev_b32_e32 v4, 16, v4
	v_add3_u32 v5, v38, v5, s17
	v_and_or_b32 v4, v5, s18, v4
	s_waitcnt lgkmcnt(1)
	v_bfe_u32 v5, v40, 16, 1
	v_add3_u32 v5, v40, v5, s17
	s_waitcnt lgkmcnt(0)
	v_bfe_u32 v6, v42, 16, 1
	v_lshrrev_b32_e32 v5, 16, v5
	v_add3_u32 v6, v42, v6, s17
	s_lshl_b32 s0, s13, 1
	v_and_or_b32 v5, v6, s18, v5
	v_or_b32_e32 v6, s12, v74
	v_lshl_add_u64 v[8:9], v[18:19], 0, s[0:1]
	v_lshlrev_b32_e32 v12, 13, v6
	v_lshl_add_u64 v[44:45], v[8:9], 0, v[12:13]
	global_store_dwordx4 v[44:45], v[2:5], off nt
	v_bfe_u32 v6, v43, 16, 1
	v_or_b32_e32 v12, s12, v76
	v_bfe_u32 v2, v7, 16, 1
	v_add3_u32 v2, v7, v2, s17
	v_bfe_u32 v3, v31, 16, 1
	v_lshrrev_b32_e32 v2, 16, v2
	v_add3_u32 v3, v31, v3, s17
	v_and_or_b32 v2, v3, s18, v2
	v_bfe_u32 v3, v33, 16, 1
	v_add3_u32 v3, v33, v3, s17
	v_bfe_u32 v4, v35, 16, 1
	v_lshrrev_b32_e32 v3, 16, v3
	v_add3_u32 v4, v35, v4, s17
	v_and_or_b32 v3, v4, s18, v3
	v_bfe_u32 v4, v37, 16, 1
	v_add3_u32 v4, v37, v4, s17
	v_bfe_u32 v5, v39, 16, 1
	v_lshrrev_b32_e32 v4, 16, v4
	v_add3_u32 v5, v39, v5, s17
	v_and_or_b32 v4, v5, s18, v4
	v_bfe_u32 v5, v41, 16, 1
	v_add3_u32 v5, v41, v5, s17
	v_lshrrev_b32_e32 v5, 16, v5
	v_add3_u32 v6, v43, v6, s17
	v_lshlrev_b32_e32 v12, 13, v12
	v_and_or_b32 v5, v6, s18, v5
	ds_read2_b32 v[6:7], v17 offset0:16 offset1:24
	v_lshl_add_u64 v[30:31], v[8:9], 0, v[12:13]
	global_store_dwordx4 v[30:31], v[2:5], off nt
	ds_read2_b32 v[30:31], v17 offset0:49 offset1:57
	ds_read2_b32 v[32:33], v17 offset0:82 offset1:90
	ds_read2_b32 v[34:35], v17 offset0:115 offset1:123
	s_waitcnt lgkmcnt(3)
	v_bfe_u32 v2, v6, 16, 1
	v_add3_u32 v2, v6, v2, s17
	s_waitcnt lgkmcnt(2)
	v_bfe_u32 v3, v30, 16, 1
	ds_read2_b32 v[36:37], v17 offset0:148 offset1:156
	v_lshrrev_b32_e32 v2, 16, v2
	v_add3_u32 v3, v30, v3, s17
	ds_read2_b32 v[38:39], v17 offset0:181 offset1:189
	v_and_or_b32 v2, v3, s18, v2
	s_waitcnt lgkmcnt(3)
	v_bfe_u32 v3, v32, 16, 1
	v_add3_u32 v3, v32, v3, s17
	s_waitcnt lgkmcnt(2)
	v_bfe_u32 v4, v34, 16, 1
	ds_read2_b32 v[40:41], v17 offset0:214 offset1:222
	v_lshrrev_b32_e32 v3, 16, v3
	v_add3_u32 v4, v34, v4, s17
	ds_read2_b32 v[42:43], v17 offset0:247 offset1:255
	v_and_or_b32 v3, v4, s18, v3
	s_waitcnt lgkmcnt(3)
	v_bfe_u32 v4, v36, 16, 1
	v_add3_u32 v4, v36, v4, s17
	s_waitcnt lgkmcnt(2)
	v_bfe_u32 v5, v38, 16, 1
	v_lshrrev_b32_e32 v4, 16, v4
	v_add3_u32 v5, v38, v5, s17
	v_and_or_b32 v4, v5, s18, v4
	s_waitcnt lgkmcnt(1)
	v_bfe_u32 v5, v40, 16, 1
	v_add3_u32 v5, v40, v5, s17
	s_waitcnt lgkmcnt(0)
	v_bfe_u32 v6, v42, 16, 1
	v_lshrrev_b32_e32 v5, 16, v5
	v_add3_u32 v6, v42, v6, s17
	v_and_or_b32 v5, v6, s18, v5
	v_or_b32_e32 v6, s12, v77
	v_lshlrev_b32_e32 v12, 13, v6
	v_lshl_add_u64 v[44:45], v[8:9], 0, v[12:13]
	global_store_dwordx4 v[44:45], v[2:5], off nt
	v_bfe_u32 v6, v43, 16, 1
	v_add3_u32 v6, v43, v6, s17
	v_bfe_u32 v2, v7, 16, 1
	v_add3_u32 v2, v7, v2, s17
	v_bfe_u32 v3, v31, 16, 1
	v_lshrrev_b32_e32 v2, 16, v2
	v_add3_u32 v3, v31, v3, s17
	v_and_or_b32 v2, v3, s18, v2
	v_bfe_u32 v3, v33, 16, 1
	v_add3_u32 v3, v33, v3, s17
	v_bfe_u32 v4, v35, 16, 1
	v_lshrrev_b32_e32 v3, 16, v3
	v_add3_u32 v4, v35, v4, s17
	v_and_or_b32 v3, v4, s18, v3
	v_bfe_u32 v4, v37, 16, 1
	v_add3_u32 v4, v37, v4, s17
	v_bfe_u32 v5, v39, 16, 1
	v_lshrrev_b32_e32 v4, 16, v4
	v_add3_u32 v5, v39, v5, s17
	v_and_or_b32 v4, v5, s18, v4
	v_bfe_u32 v5, v41, 16, 1
	v_add3_u32 v5, v41, v5, s17
	v_lshrrev_b32_e32 v5, 16, v5
	v_and_or_b32 v5, v6, s18, v5
	v_or_b32_e32 v6, s12, v78
	v_lshlrev_b32_e32 v12, 13, v6
	v_lshl_add_u64 v[6:7], v[8:9], 0, v[12:13]
	global_store_dwordx4 v[6:7], v[2:5], off nt
	s_waitcnt lgkmcnt(0)
	s_mov_b64 s[12:13], 0

.LBB0_689:
	s_lshl_b32 s28, s15, 1
	s_lshl_b32 s23, s13, 1
	v_or_b32_e32 v45, s28, v10
	s_add_i32 s30, s28, 4
	v_or_b32_e32 v44, s23, v1
	s_add_i32 s29, s23, 4
	s_add_i32 s31, s23, 8
	s_add_i32 s33, s28, 8
	s_add_i32 s34, s23, 12
	s_add_i32 s36, s23, 16
	s_add_i32 s38, s23, 20
	s_add_i32 s40, s23, 24
	s_add_i32 s23, s23, 28
	v_add_lshl_u32 v6, v45, s12, 12
	v_or_b32_e32 v47, s30, v10
	s_add_i32 s35, s28, 12
	v_add_lshl_u32 v4, v44, s14, 12
	v_or_b32_e32 v46, s29, v1
	v_or_b32_e32 v48, s31, v1
	v_or_b32_e32 v49, s33, v10
	v_or_b32_e32 v50, s34, v1
	v_or_b32_e32 v52, s36, v1
	v_or_b32_e32 v54, s38, v1
	v_or_b32_e32 v56, s40, v1
	v_or_b32_e32 v58, s23, v1
	v_or_b32_e32 v12, v2, v6
	v_add_lshl_u32 v8, v47, s12, 12
	v_mov_b32_e32 v5, v13
	s_add_i32 s37, s28, 16
	v_or_b32_e32 v51, s35, v10
	v_or_b32_e32 v4, v3, v4
	v_add_lshl_u32 v6, v46, s14, 12
	v_add_lshl_u32 v30, v48, s14, 12
	v_add_lshl_u32 v60, v49, s12, 12
	v_add_lshl_u32 v32, v50, s14, 12
	v_add_lshl_u32 v34, v52, s14, 12
	v_add_lshl_u32 v36, v54, s14, 12
	v_add_lshl_u32 v38, v56, s14, 12
	v_add_lshl_u32 v42, v58, s14, 12
	v_lshl_add_u64 v[40:41], v[12:13], 2, s[82:83]
	v_or_b32_e32 v12, v2, v8
	v_mov_b32_e32 v7, v13
	s_add_i32 s39, s28, 20
	v_or_b32_e32 v53, s37, v10
	v_add_lshl_u32 v61, v51, s12, 12
	v_lshl_add_u64 v[4:5], v[4:5], 2, s[82:83]
	v_or_b32_e32 v6, v3, v6
	v_or_b32_e32 v8, v3, v30
	v_or_b32_e32 v30, v3, v32
	v_or_b32_e32 v32, v3, v34
	v_or_b32_e32 v34, v3, v36
	v_or_b32_e32 v36, v3, v38
	v_or_b32_e32 v38, v3, v42
	v_lshl_add_u64 v[42:43], v[12:13], 2, s[82:83]
	v_or_b32_e32 v12, v2, v60
	s_add_i32 s41, s28, 24
	v_or_b32_e32 v55, s39, v10
	v_add_lshl_u32 v62, v53, s12, 12
	v_lshl_add_u64 v[6:7], v[6:7], 2, s[82:83]
	global_load_dword v60, v[40:41], off nt
	global_load_dword v66, v[4:5], off nt
	global_load_dword v67, v[42:43], off nt
	global_load_dword v68, v[6:7], off nt
	v_lshl_add_u64 v[4:5], v[12:13], 2, s[82:83]
	v_or_b32_e32 v12, v2, v61
	v_mov_b32_e32 v9, v13
	v_mov_b32_e32 v31, v13
	s_add_i32 s28, s28, 28
	v_or_b32_e32 v57, s41, v10
	v_add_lshl_u32 v63, v55, s12, 12
	v_lshl_add_u64 v[6:7], v[12:13], 2, s[82:83]
	v_or_b32_e32 v12, v2, v62
	v_or_b32_e32 v59, s28, v10
	v_add_lshl_u32 v64, v57, s12, 12
	v_lshl_add_u64 v[8:9], v[8:9], 2, s[82:83]
	v_lshl_add_u64 v[30:31], v[30:31], 2, s[82:83]
	global_load_dword v61, v[4:5], off nt
	global_load_dword v62, v[8:9], off nt
	global_load_dword v69, v[6:7], off nt
	global_load_dword v70, v[30:31], off nt
	v_lshl_add_u64 v[4:5], v[12:13], 2, s[82:83]
	v_or_b32_e32 v12, v2, v63
	v_mov_b32_e32 v33, v13
	v_mov_b32_e32 v35, v13
	v_add_lshl_u32 v65, v59, s12, 12
	v_lshl_add_u64 v[6:7], v[12:13], 2, s[82:83]
	v_or_b32_e32 v12, v2, v64
	v_mov_b32_e32 v37, v13
	v_mov_b32_e32 v39, v13
	v_lshl_add_u64 v[32:33], v[32:33], 2, s[82:83]
	v_lshl_add_u64 v[34:35], v[34:35], 2, s[82:83]
	global_load_dword v63, v[4:5], off nt
	global_load_dword v64, v[32:33], off nt
	global_load_dword v71, v[6:7], off nt
	global_load_dword v72, v[34:35], off nt
	v_lshl_add_u64 v[4:5], v[12:13], 2, s[82:83]
	v_or_b32_e32 v12, v2, v65
	v_lshl_add_u64 v[36:37], v[36:37], 2, s[82:83]
	v_lshl_add_u64 v[38:39], v[38:39], 2, s[82:83]
	v_lshl_add_u64 v[6:7], v[12:13], 2, s[82:83]
	global_load_dword v12, v[4:5], off nt
	global_load_dword v65, v[36:37], off nt
	global_load_dword v73, v[6:7], off nt
	global_load_dword v79, v[38:39], off nt
	s_add_i32 s15, s15, 16
	s_add_i32 s13, s13, 16
	s_add_i32 s22, s22, -16
	v_mad_u64_u32 v[4:5], s[28:29], v45, s3, v[16:17]
	s_cmp_lg_u32 s22, 0
	v_mad_u64_u32 v[6:7], s[28:29], v44, s3, v[16:17]
	v_mad_u64_u32 v[8:9], s[28:29], v47, s3, v[16:17]
	v_mad_u64_u32 v[30:31], s[28:29], v46, s3, v[16:17]
	v_mad_u64_u32 v[32:33], s[28:29], v49, s3, v[16:17]
	v_mad_u64_u32 v[34:35], s[28:29], v48, s3, v[16:17]
	v_mad_u64_u32 v[36:37], s[28:29], v51, s3, v[16:17]
	v_mad_u64_u32 v[38:39], s[28:29], v50, s3, v[16:17]
	v_mad_u64_u32 v[40:41], s[28:29], v53, s3, v[16:17]
	v_mad_u64_u32 v[42:43], s[28:29], v52, s3, v[16:17]
	v_mad_u64_u32 v[44:45], s[28:29], v55, s3, v[16:17]
	v_mad_u64_u32 v[46:47], s[28:29], v54, s3, v[16:17]
	v_mad_u64_u32 v[48:49], s[28:29], v57, s3, v[16:17]
	v_mad_u64_u32 v[50:51], s[28:29], v56, s3, v[16:17]
	v_mad_u64_u32 v[52:53], s[28:29], v59, s3, v[16:17]
	v_mad_u64_u32 v[54:55], s[28:29], v58, s3, v[16:17]
	s_waitcnt vmcnt(15)
	ds_write_b32 v4, v60
	s_waitcnt vmcnt(14)
	ds_write_b32 v6, v66
	s_waitcnt vmcnt(13)
	ds_write_b32 v8, v67
	s_waitcnt vmcnt(12)
	ds_write_b32 v30, v68
	s_waitcnt vmcnt(11)
	ds_write_b32 v32, v61
	s_waitcnt vmcnt(10)
	ds_write_b32 v34, v62
	s_waitcnt vmcnt(9)
	ds_write_b32 v36, v69
	s_waitcnt vmcnt(8)
	ds_write_b32 v38, v70
	s_waitcnt vmcnt(7)
	ds_write_b32 v40, v63
	s_waitcnt vmcnt(6)
	ds_write_b32 v42, v64
	s_waitcnt vmcnt(5)
	ds_write_b32 v44, v71
	s_waitcnt vmcnt(4)
	ds_write_b32 v46, v72
	s_waitcnt vmcnt(3)
	ds_write_b32 v48, v12
	s_waitcnt vmcnt(2)
	ds_write_b32 v50, v65
	s_waitcnt vmcnt(1)
	ds_write_b32 v52, v73
	s_waitcnt vmcnt(0)
	ds_write_b32 v54, v79
	s_cbranch_scc1 .LBB0_689
	v_or_b32_e32 v12, s12, v11
	s_waitcnt lgkmcnt(0)
	v_lshlrev_b64 v[30:31], 2, v[12:13]
	v_readlane_b32 s48, v253, 4
	v_lshl_add_u64 v[2:3], s[4:5], 0, v[30:31]
	v_readlane_b32 s62, v253, 18
	v_readlane_b32 s63, v253, 19
	global_load_dwordx4 v[32:35], v[2:3], off
	v_lshl_add_u64 v[44:45], s[6:7], 0, v[30:31]
	v_lshl_add_u64 v[4:5], s[62:63], 0, v[30:31]
	global_load_dwordx4 v[6:9], v[4:5], off
	global_load_dwordx4 v[36:39], v[2:3], off offset:16
	s_nop 0
	global_load_dwordx4 v[2:5], v[4:5], off offset:16
	s_nop 0
	global_load_dwordx4 v[40:43], v[44:45], off
	s_nop 0
	global_load_dwordx4 v[44:47], v[44:45], off offset:16
	v_readlane_b32 s12, v253, 40
	v_or_b32_e32 v50, s0, v74
	v_lshlrev_b32_e32 v12, 1, v12
	v_lshl_add_u64 v[48:49], s[8:9], 0, v[30:31]
	v_readlane_b32 s13, v253, 41
	v_lshl_add_u64 v[54:55], s[10:11], 0, v[30:31]
	ds_read2_b32 v[70:71], v17 offset1:8
	ds_read2_b32 v[66:67], v17 offset0:33 offset1:41
	ds_read2_b32 v[58:59], v17 offset0:66 offset1:74
	ds_read2_b32 v[56:57], v17 offset0:99 offset1:107
	ds_read2_b32 v[68:69], v17 offset0:132 offset1:140
	ds_read2_b32 v[64:65], v17 offset0:165 offset1:173
	ds_read2_b32 v[62:63], v17 offset0:198 offset1:206
	ds_read2_b32 v[60:61], v17 offset0:231 offset1:239
	v_lshl_add_u64 v[30:31], s[12:13], 0, v[12:13]
	v_lshlrev_b32_e32 v12, 11, v50
	global_load_dwordx4 v[50:53], v[48:49], off offset:16
	global_load_dwordx4 v[80:83], v[48:49], off
	global_load_dwordx4 v[84:87], v[54:55], off offset:16
	global_load_dwordx4 v[88:91], v[54:55], off
	s_waitcnt lgkmcnt(6)
	v_mov_b32_e32 v98, v66
	s_waitcnt lgkmcnt(4)
	v_mov_b32_e32 v99, v56
	s_waitcnt lgkmcnt(3)
	v_mov_b32_e32 v100, v68
	s_waitcnt lgkmcnt(1)
	v_mov_b32_e32 v101, v62
	v_mov_b32_e32 v96, v70
	v_mov_b32_e32 v97, v58
	v_mov_b32_e32 v102, v64
	s_waitcnt lgkmcnt(0)
	v_mov_b32_e32 v103, v60
	v_lshl_add_u64 v[72:73], v[30:31], 0, v[12:13]
	v_readlane_b32 s49, v253, 5
	v_readlane_b32 s54, v253, 10
	v_readlane_b32 s55, v253, 11
	v_readlane_b32 s56, v253, 12
	v_readlane_b32 s48, v252, 4
	v_readlane_b32 s54, v253, 20
	s_mov_b32 s55, s42
	s_mov_b32 s56, s43
	v_readlane_b32 s49, v252, 5
	v_readlane_b32 s50, v253, 6
	v_readlane_b32 s51, v253, 7
	v_readlane_b32 s52, v253, 8
	v_readlane_b32 s53, v253, 9
	v_readlane_b32 s57, v253, 13
	v_readlane_b32 s58, v253, 14
	v_readlane_b32 s59, v253, 15
	v_readlane_b32 s60, v253, 16
	v_readlane_b32 s61, v253, 17
	s_waitcnt vmcnt(9)
	v_mov_b32_e32 v48, v32
	v_mov_b32_e32 v49, v34
	s_waitcnt vmcnt(8)
	v_mov_b32_e32 v104, v6
	v_mov_b32_e32 v105, v8
	v_mov_b32_e32 v34, v33
	v_mov_b32_e32 v8, v7
	s_waitcnt vmcnt(7)
	v_mov_b32_e32 v6, v36
	v_mov_b32_e32 v7, v38
	s_waitcnt vmcnt(6)
	v_mov_b32_e32 v106, v2
	v_mov_b32_e32 v107, v4
	v_mov_b32_e32 v38, v37
	v_pk_add_f32 v[32:33], v[48:49], 1.0 op_sel_hi:[1,0]
	v_pk_add_f32 v[34:35], v[34:35], 1.0 op_sel_hi:[1,0]
	v_pk_add_f32 v[6:7], v[6:7], 1.0 op_sel_hi:[1,0]
	v_mov_b32_e32 v4, v3
	s_waitcnt vmcnt(5)
	v_mov_b32_e32 v2, v40
	v_mov_b32_e32 v3, v42
	v_pk_add_f32 v[48:49], v[38:39], 1.0 op_sel_hi:[1,0]
	v_pk_mul_f32 v[38:39], v[104:105], v[32:33]
	v_pk_mul_f32 v[36:37], v[8:9], v[34:35]
	v_pk_mul_f32 v[32:33], v[106:107], v[6:7]
	v_pk_add_f32 v[54:55], v[2:3], 1.0 op_sel_hi:[1,0]
	v_pk_mul_f32 v[2:3], v[4:5], v[48:49]
	v_pk_mul_f32 v[34:35], v[36:37], v[98:99]
	v_pk_mul_f32 v[48:49], v[32:33], v[100:101]
	v_pk_mul_f32 v[6:7], v[38:39], v[96:97]
	v_pk_mul_f32 v[92:93], v[2:3], v[102:103]
	v_bfe_u32 v42, v35, 16, 1
	v_bfe_u32 v64, v49, 16, 1
	v_bfe_u32 v12, v93, 16, 1
	v_bfe_u32 v58, v6, 16, 1
	v_bfe_u32 v60, v7, 16, 1
	v_bfe_u32 v62, v48, 16, 1
	v_add3_u32 v35, v35, v42, s17
	v_add3_u32 v42, v49, v64, s17
	v_bfe_u32 v40, v92, 16, 1
	v_bfe_u32 v56, v34, 16, 1
	v_add3_u32 v12, v93, v12, s17
	v_add3_u32 v48, v48, v62, s17
	v_add3_u32 v7, v7, v60, s17
	v_add3_u32 v6, v6, v58, s17
	v_lshrrev_b32_e32 v42, 16, v42
	v_add3_u32 v34, v34, v56, s17
	v_add3_u32 v40, v92, v40, s17
	v_lshrrev_b32_e32 v6, 16, v6
	v_lshrrev_b32_e32 v7, 16, v7
	v_lshrrev_b32_e32 v48, 16, v48
	v_and_or_b32 v95, v12, s18, v42
	v_mov_b32_e32 v42, v41
	s_waitcnt vmcnt(4)
	v_mov_b32_e32 v41, v46
	v_mov_b32_e32 v46, v45
	v_and_or_b32 v94, v40, s18, v48
	v_and_or_b32 v93, v35, s18, v7
	v_and_or_b32 v92, v34, s18, v6
	v_pk_add_f32 v[34:35], v[42:43], 1.0 op_sel_hi:[1,0]
	v_mov_b32_e32 v40, v44
	v_pk_add_f32 v[42:43], v[46:47], 1.0 op_sel_hi:[1,0]
	v_pk_mul_f32 v[34:35], v[8:9], v[34:35]
	v_pk_add_f32 v[40:41], v[40:41], 1.0 op_sel_hi:[1,0]
	v_pk_mul_f32 v[42:43], v[4:5], v[42:43]
	v_pk_mul_f32 v[6:7], v[104:105], v[54:55]
	v_pk_mul_f32 v[54:55], v[34:35], v[98:99]
	v_pk_mul_f32 v[40:41], v[106:107], v[40:41]
	v_pk_mul_f32 v[46:47], v[42:43], v[102:103]
	v_pk_mul_f32 v[48:49], v[6:7], v[96:97]
	v_pk_mul_f32 v[44:45], v[40:41], v[100:101]
	v_bfe_u32 v12, v47, 16, 1
	v_bfe_u32 v58, v55, 16, 1
	v_bfe_u32 v56, v46, 16, 1
	v_bfe_u32 v60, v54, 16, 1
	v_add3_u32 v55, v55, v58, s17
	v_add3_u32 v12, v47, v12, s17
	v_bfe_u32 v47, v48, 16, 1
	v_bfe_u32 v58, v44, 16, 1
	v_add3_u32 v54, v54, v60, s17
	v_add3_u32 v46, v46, v56, s17
	v_bfe_u32 v56, v49, 16, 1
	v_bfe_u32 v60, v45, 16, 1
	v_add3_u32 v44, v44, v58, s17
	v_add3_u32 v47, v48, v47, s17
	v_add3_u32 v45, v45, v60, s17
	v_add3_u32 v49, v49, v56, s17
	v_lshrrev_b32_e32 v48, 16, v47
	v_lshrrev_b32_e32 v44, 16, v44
	v_lshrrev_b32_e32 v49, 16, v49
	v_lshrrev_b32_e32 v45, 16, v45
	v_and_or_b32 v46, v46, s18, v44
	v_and_or_b32 v44, v54, s18, v48
	v_add_co_u32_e32 v48, vcc, s19, v72
	v_and_or_b32 v47, v12, s18, v45
	v_and_or_b32 v45, v55, s18, v49
	v_addc_co_u32_e32 v49, vcc, 0, v73, vcc
	global_store_dwordx4 v[48:49], v[44:47], off nt
	s_waitcnt vmcnt(4)
	v_mov_b32_e32 v48, v50
	v_mov_b32_e32 v49, v52
	s_waitcnt vmcnt(3)
	v_mov_b32_e32 v44, v80
	v_mov_b32_e32 v45, v82
	v_pk_add_f32 v[44:45], v[44:45], 1.0 op_sel_hi:[1,0]
	v_mov_b32_e32 v82, v81
	v_pk_add_f32 v[48:49], v[48:49], 1.0 op_sel_hi:[1,0]
	v_mov_b32_e32 v52, v51
	v_pk_mul_f32 v[44:45], v[104:105], v[44:45]
	v_pk_add_f32 v[46:47], v[82:83], 1.0 op_sel_hi:[1,0]
	v_pk_mul_f32 v[48:49], v[106:107], v[48:49]
	v_pk_add_f32 v[50:51], v[52:53], 1.0 op_sel_hi:[1,0]
	v_pk_mul_f32 v[46:47], v[8:9], v[46:47]
	v_pk_mul_f32 v[54:55], v[44:45], v[96:97]
	v_pk_mul_f32 v[50:51], v[4:5], v[50:51]
	v_pk_mul_f32 v[52:53], v[48:49], v[100:101]
	v_pk_mul_f32 v[80:81], v[46:47], v[98:99]
	v_pk_mul_f32 v[82:83], v[50:51], v[102:103]
	v_bfe_u32 v62, v54, 16, 1
	v_bfe_u32 v64, v55, 16, 1
	v_bfe_u32 v66, v52, 16, 1
	v_bfe_u32 v68, v53, 16, 1
	v_bfe_u32 v12, v83, 16, 1
	v_bfe_u32 v56, v82, 16, 1
	v_bfe_u32 v58, v81, 16, 1
	v_bfe_u32 v60, v80, 16, 1
	v_add3_u32 v53, v53, v68, s17
	v_add3_u32 v52, v52, v66, s17
	v_add3_u32 v55, v55, v64, s17
	v_add3_u32 v54, v54, v62, s17
	v_add3_u32 v60, v80, v60, s17
	v_add3_u32 v58, v81, v58, s17
	v_add3_u32 v56, v82, v56, s17
	v_add3_u32 v12, v83, v12, s17
	v_lshrrev_b32_e32 v62, 16, v54
	v_lshrrev_b32_e32 v64, 16, v55
	v_lshrrev_b32_e32 v52, 16, v52
	v_lshrrev_b32_e32 v53, 16, v53
	v_add_co_u32_e32 v80, vcc, s20, v72
	v_and_or_b32 v55, v12, s18, v53
	v_and_or_b32 v54, v56, s18, v52
	v_and_or_b32 v53, v58, s18, v64
	v_and_or_b32 v52, v60, s18, v62
	v_addc_co_u32_e32 v81, vcc, 0, v73, vcc
	global_store_dwordx4 v[80:81], v[52:55], off nt
	global_store_dwordx4 v[72:73], v[92:95], off nt
	v_add_co_u32_e32 v72, vcc, s21, v72
	s_waitcnt vmcnt(3)
	v_mov_b32_e32 v53, v90
	v_mov_b32_e32 v90, v89
	v_pk_add_f32 v[54:55], v[90:91], 1.0 op_sel_hi:[1,0]
	v_mov_b32_e32 v52, v88
	v_pk_mul_f32 v[8:9], v[8:9], v[54:55]
	v_mov_b32_e32 v54, v84
	v_mov_b32_e32 v55, v86
	v_pk_add_f32 v[52:53], v[52:53], 1.0 op_sel_hi:[1,0]
	v_pk_add_f32 v[54:55], v[54:55], 1.0 op_sel_hi:[1,0]
	v_mov_b32_e32 v86, v85
	v_pk_mul_f32 v[52:53], v[104:105], v[52:53]
	v_pk_mul_f32 v[54:55], v[106:107], v[54:55]
	v_pk_add_f32 v[84:85], v[86:87], 1.0 op_sel_hi:[1,0]
	v_pk_mul_f32 v[80:81], v[96:97], v[52:53]
	v_pk_mul_f32 v[4:5], v[4:5], v[84:85]
	v_pk_mul_f32 v[84:85], v[54:55], v[100:101]
	v_pk_mul_f32 v[82:83], v[98:99], v[8:9]
	v_pk_mul_f32 v[86:87], v[4:5], v[102:103]
	v_bfe_u32 v62, v80, 16, 1
	v_bfe_u32 v66, v84, 16, 1
	v_bfe_u32 v68, v85, 16, 1
	v_bfe_u32 v12, v87, 16, 1
	v_bfe_u32 v56, v86, 16, 1
	v_bfe_u32 v60, v82, 16, 1
	v_bfe_u32 v64, v81, 16, 1
	v_add3_u32 v68, v85, v68, s17
	v_add3_u32 v66, v84, v66, s17
	v_add3_u32 v62, v80, v62, s17
	v_bfe_u32 v58, v83, 16, 1
	v_add3_u32 v60, v82, v60, s17
	v_add3_u32 v56, v86, v56, s17
	v_add3_u32 v12, v87, v12, s17
	v_add3_u32 v64, v81, v64, s17
	v_lshrrev_b32_e32 v62, 16, v62
	v_lshrrev_b32_e32 v66, 16, v66
	v_lshrrev_b32_e32 v68, 16, v68
	v_add3_u32 v58, v83, v58, s17
	v_lshrrev_b32_e32 v64, 16, v64
	v_and_or_b32 v83, v12, s18, v68
	v_and_or_b32 v82, v56, s18, v66
	v_and_or_b32 v80, v60, s18, v62
	v_or_b32_e32 v12, s0, v76
	v_mov_b32_e32 v56, v67
	v_mov_b32_e32 v60, v65
	v_and_or_b32 v81, v58, s18, v64
	v_addc_co_u32_e32 v73, vcc, 0, v73, vcc
	v_lshlrev_b32_e32 v12, 11, v12
	v_mov_b32_e32 v58, v71
	v_pk_mul_f32 v[66:67], v[36:37], v[56:57]
	v_mov_b32_e32 v62, v69
	v_pk_mul_f32 v[64:65], v[2:3], v[60:61]
	global_store_dwordx4 v[72:73], v[80:83], off nt
	v_lshl_add_u64 v[72:73], v[30:31], 0, v[12:13]
	v_pk_mul_f32 v[70:71], v[38:39], v[58:59]
	v_pk_mul_f32 v[68:69], v[32:33], v[62:63]
	v_bfe_u32 v12, v65, 16, 1
	v_bfe_u32 v79, v64, 16, 1
	v_bfe_u32 v80, v67, 16, 1
	v_bfe_u32 v81, v66, 16, 1
	v_add3_u32 v81, v66, v81, s17
	v_add3_u32 v80, v67, v80, s17
	v_add3_u32 v64, v64, v79, s17
	v_add3_u32 v12, v65, v12, s17
	v_bfe_u32 v65, v70, 16, 1
	v_bfe_u32 v66, v71, 16, 1
	v_bfe_u32 v67, v68, 16, 1
	v_bfe_u32 v79, v69, 16, 1
	v_add3_u32 v69, v69, v79, s17
	v_add3_u32 v67, v68, v67, s17
	v_add3_u32 v66, v71, v66, s17
	v_add3_u32 v65, v70, v65, s17
	v_lshrrev_b32_e32 v68, 16, v65
	v_lshrrev_b32_e32 v65, 16, v66
	v_lshrrev_b32_e32 v66, 16, v67
	v_lshrrev_b32_e32 v67, 16, v69
	v_and_or_b32 v67, v12, s18, v67
	v_and_or_b32 v66, v64, s18, v66
	v_and_or_b32 v65, v80, s18, v65
	v_and_or_b32 v64, v81, s18, v68
	v_pk_mul_f32 v[70:71], v[42:43], v[60:61]
	global_store_dwordx4 v[72:73], v[64:67], off nt
	v_pk_mul_f32 v[68:69], v[40:41], v[62:63]
	v_bfe_u32 v12, v71, 16, 1
	v_pk_mul_f32 v[66:67], v[34:35], v[56:57]
	v_pk_mul_f32 v[64:65], v[6:7], v[58:59]
	v_bfe_u32 v79, v70, 16, 1
	v_bfe_u32 v80, v67, 16, 1
	v_bfe_u32 v81, v66, 16, 1
	v_add3_u32 v12, v71, v12, s17
	v_bfe_u32 v71, v68, 16, 1
	v_add3_u32 v81, v66, v81, s17
	v_add3_u32 v80, v67, v80, s17
	v_add3_u32 v66, v70, v79, s17
	v_bfe_u32 v67, v64, 16, 1
	v_bfe_u32 v70, v65, 16, 1
	v_bfe_u32 v79, v69, 16, 1
	v_add3_u32 v68, v68, v71, s17
	v_add3_u32 v69, v69, v79, s17
	v_add3_u32 v65, v65, v70, s17
	v_add3_u32 v64, v64, v67, s17
	v_lshrrev_b32_e32 v68, 16, v68
	v_lshrrev_b32_e32 v64, 16, v64
	v_lshrrev_b32_e32 v65, 16, v65
	v_lshrrev_b32_e32 v67, 16, v69
	v_and_or_b32 v66, v66, s18, v68
	v_add_co_u32_e32 v68, vcc, s19, v72
	v_and_or_b32 v67, v12, s18, v67
	v_and_or_b32 v65, v80, s18, v65
	v_and_or_b32 v64, v81, s18, v64
	v_addc_co_u32_e32 v69, vcc, 0, v73, vcc
	v_pk_mul_f32 v[70:71], v[50:51], v[60:61]
	global_store_dwordx4 v[68:69], v[64:67], off nt
	v_pk_mul_f32 v[68:69], v[48:49], v[62:63]
	v_bfe_u32 v12, v71, 16, 1
	v_pk_mul_f32 v[66:67], v[46:47], v[56:57]
	v_pk_mul_f32 v[64:65], v[44:45], v[58:59]
	v_bfe_u32 v79, v70, 16, 1
	v_bfe_u32 v80, v67, 16, 1
	v_bfe_u32 v81, v66, 16, 1
	v_add3_u32 v12, v71, v12, s17
	v_bfe_u32 v71, v68, 16, 1
	v_add3_u32 v81, v66, v81, s17
	v_add3_u32 v80, v67, v80, s17
	v_add3_u32 v66, v70, v79, s17
	v_bfe_u32 v67, v64, 16, 1
	v_bfe_u32 v70, v65, 16, 1
	v_bfe_u32 v79, v69, 16, 1
	v_add3_u32 v68, v68, v71, s17
	v_add3_u32 v69, v69, v79, s17
	v_add3_u32 v65, v65, v70, s17
	v_add3_u32 v64, v64, v67, s17
	v_lshrrev_b32_e32 v68, 16, v68
	v_lshrrev_b32_e32 v64, 16, v64
	v_lshrrev_b32_e32 v65, 16, v65
	v_lshrrev_b32_e32 v67, 16, v69
	v_and_or_b32 v66, v66, s18, v68
	v_add_co_u32_e32 v68, vcc, s20, v72
	v_and_or_b32 v67, v12, s18, v67
	v_and_or_b32 v65, v80, s18, v65
	v_and_or_b32 v64, v81, s18, v64
	v_addc_co_u32_e32 v69, vcc, 0, v73, vcc
	v_pk_mul_f32 v[56:57], v[8:9], v[56:57]
	v_pk_mul_f32 v[60:61], v[4:5], v[60:61]
	global_store_dwordx4 v[68:69], v[64:67], off nt
	v_pk_mul_f32 v[58:59], v[52:53], v[58:59]
	v_pk_mul_f32 v[62:63], v[54:55], v[62:63]
	v_bfe_u32 v12, v61, 16, 1
	v_bfe_u32 v65, v57, 16, 1
	v_bfe_u32 v64, v60, 16, 1
	v_bfe_u32 v66, v56, 16, 1
	v_add3_u32 v57, v57, v65, s17
	v_add3_u32 v12, v61, v12, s17
	v_bfe_u32 v61, v58, 16, 1
	v_bfe_u32 v65, v62, 16, 1
	v_add3_u32 v56, v56, v66, s17
	v_add3_u32 v60, v60, v64, s17
	v_bfe_u32 v64, v59, 16, 1
	v_bfe_u32 v66, v63, 16, 1
	v_add3_u32 v62, v62, v65, s17
	v_add3_u32 v58, v58, v61, s17
	v_add3_u32 v63, v63, v66, s17
	v_add3_u32 v59, v59, v64, s17
	v_lshrrev_b32_e32 v61, 16, v58
	v_lshrrev_b32_e32 v58, 16, v62
	v_lshrrev_b32_e32 v64, 16, v59
	v_lshrrev_b32_e32 v59, 16, v63
	v_and_or_b32 v58, v60, s18, v58
	v_add_co_u32_e32 v60, vcc, s21, v72
	v_and_or_b32 v59, v12, s18, v59
	v_and_or_b32 v57, v57, s18, v64
	v_and_or_b32 v56, v56, s18, v61
	v_addc_co_u32_e32 v61, vcc, 0, v73, vcc
	global_store_dwordx4 v[60:61], v[56:59], off nt
	ds_read2_b32 v[68:69], v17 offset0:16 offset1:24
	ds_read2_b32 v[70:71], v17 offset0:49 offset1:57
	ds_read2_b32 v[56:57], v17 offset0:82 offset1:90
	ds_read2_b32 v[58:59], v17 offset0:115 offset1:123
	ds_read2_b32 v[72:73], v17 offset0:148 offset1:156
	ds_read2_b32 v[80:81], v17 offset0:181 offset1:189
	ds_read2_b32 v[60:61], v17 offset0:214 offset1:222
	ds_read2_b32 v[62:63], v17 offset0:247 offset1:255
	s_waitcnt lgkmcnt(6)
	v_mov_b32_e32 v86, v70
	s_waitcnt lgkmcnt(4)
	v_mov_b32_e32 v87, v58
	v_mov_b32_e32 v84, v68
	v_mov_b32_e32 v85, v56
	v_pk_mul_f32 v[66:67], v[36:37], v[86:87]
	s_waitcnt lgkmcnt(3)
	v_mov_b32_e32 v88, v72
	s_waitcnt lgkmcnt(1)
	v_mov_b32_e32 v89, v60
	v_or_b32_e32 v12, s0, v77
	v_pk_mul_f32 v[64:65], v[38:39], v[84:85]
	v_pk_mul_f32 v[90:91], v[32:33], v[88:89]
	v_mov_b32_e32 v92, v80
	s_waitcnt lgkmcnt(0)
	v_mov_b32_e32 v93, v62
	v_bfe_u32 v58, v67, 16, 1
	v_bfe_u32 v60, v66, 16, 1
	v_lshlrev_b32_e32 v12, 11, v12
	v_pk_mul_f32 v[94:95], v[2:3], v[92:93]
	v_add3_u32 v60, v66, v60, s17
	v_add3_u32 v58, v67, v58, s17
	v_bfe_u32 v62, v64, 16, 1
	v_bfe_u32 v66, v65, 16, 1
	v_bfe_u32 v67, v90, 16, 1
	v_bfe_u32 v68, v91, 16, 1
	v_lshl_add_u64 v[82:83], v[30:31], 0, v[12:13]
	v_bfe_u32 v12, v95, 16, 1
	v_bfe_u32 v56, v94, 16, 1
	v_add3_u32 v68, v91, v68, s17
	v_add3_u32 v67, v90, v67, s17
	v_add3_u32 v65, v65, v66, s17
	v_add3_u32 v62, v64, v62, s17
	v_add3_u32 v56, v94, v56, s17
	v_add3_u32 v12, v95, v12, s17
	v_lshrrev_b32_e32 v62, 16, v62
	v_lshrrev_b32_e32 v64, 16, v65
	v_lshrrev_b32_e32 v65, 16, v67
	v_lshrrev_b32_e32 v66, 16, v68
	v_and_or_b32 v67, v12, s18, v66
	v_and_or_b32 v66, v56, s18, v65
	v_and_or_b32 v65, v58, s18, v64
	v_and_or_b32 v64, v60, s18, v62
	global_store_dwordx4 v[82:83], v[64:67], off nt
	v_pk_mul_f32 v[90:91], v[40:41], v[88:89]
	v_pk_mul_f32 v[94:95], v[42:43], v[92:93]
	v_pk_mul_f32 v[66:67], v[34:35], v[86:87]
	v_pk_mul_f32 v[64:65], v[6:7], v[84:85]
	v_bfe_u32 v58, v67, 16, 1
	v_bfe_u32 v60, v66, 16, 1
	v_add3_u32 v60, v66, v60, s17
	v_add3_u32 v58, v67, v58, s17
	v_bfe_u32 v62, v64, 16, 1
	v_bfe_u32 v66, v65, 16, 1
	v_bfe_u32 v67, v90, 16, 1
	v_bfe_u32 v68, v91, 16, 1
	v_bfe_u32 v12, v95, 16, 1
	v_bfe_u32 v56, v94, 16, 1
	v_add3_u32 v68, v91, v68, s17
	v_add3_u32 v67, v90, v67, s17
	v_add3_u32 v65, v65, v66, s17
	v_add3_u32 v62, v64, v62, s17
	v_add3_u32 v56, v94, v56, s17
	v_add3_u32 v12, v95, v12, s17
	v_lshrrev_b32_e32 v62, 16, v62
	v_lshrrev_b32_e32 v64, 16, v65
	v_lshrrev_b32_e32 v65, 16, v67
	v_lshrrev_b32_e32 v66, 16, v68
	v_add_co_u32_e32 v90, vcc, s19, v82
	v_and_or_b32 v67, v12, s18, v66
	v_and_or_b32 v66, v56, s18, v65
	v_and_or_b32 v65, v58, s18, v64
	v_and_or_b32 v64, v60, s18, v62
	v_addc_co_u32_e32 v91, vcc, 0, v83, vcc
	global_store_dwordx4 v[90:91], v[64:67], off nt
	v_pk_mul_f32 v[90:91], v[48:49], v[88:89]
	v_pk_mul_f32 v[94:95], v[50:51], v[92:93]
	v_pk_mul_f32 v[66:67], v[46:47], v[86:87]
	v_pk_mul_f32 v[64:65], v[44:45], v[84:85]
	v_bfe_u32 v58, v67, 16, 1
	v_bfe_u32 v60, v66, 16, 1
	v_add3_u32 v60, v66, v60, s17
	v_add3_u32 v58, v67, v58, s17
	v_bfe_u32 v62, v64, 16, 1
	v_bfe_u32 v66, v65, 16, 1
	v_bfe_u32 v67, v90, 16, 1
	v_bfe_u32 v68, v91, 16, 1
	v_bfe_u32 v12, v95, 16, 1
	v_bfe_u32 v56, v94, 16, 1
	v_add3_u32 v68, v91, v68, s17
	v_add3_u32 v67, v90, v67, s17
	v_add3_u32 v65, v65, v66, s17
	v_add3_u32 v62, v64, v62, s17
	v_add3_u32 v56, v94, v56, s17
	v_add3_u32 v12, v95, v12, s17
	v_lshrrev_b32_e32 v62, 16, v62
	v_lshrrev_b32_e32 v64, 16, v65
	v_lshrrev_b32_e32 v65, 16, v67
	v_lshrrev_b32_e32 v66, 16, v68
	v_add_co_u32_e32 v90, vcc, s20, v82
	v_and_or_b32 v67, v12, s18, v66
	v_and_or_b32 v66, v56, s18, v65
	v_and_or_b32 v65, v58, s18, v64
	v_and_or_b32 v64, v60, s18, v62
	v_addc_co_u32_e32 v91, vcc, 0, v83, vcc
	global_store_dwordx4 v[90:91], v[64:67], off nt
	v_add_co_u32_e32 v82, vcc, s21, v82
	s_nop 0
	v_pk_mul_f32 v[66:67], v[8:9], v[86:87]
	v_pk_mul_f32 v[64:65], v[52:53], v[84:85]
	v_pk_mul_f32 v[84:85], v[54:55], v[88:89]
	v_bfe_u32 v58, v67, 16, 1
	v_bfe_u32 v60, v66, 16, 1
	v_pk_mul_f32 v[86:87], v[4:5], v[92:93]
	v_add3_u32 v60, v66, v60, s17
	v_add3_u32 v58, v67, v58, s17
	v_bfe_u32 v62, v64, 16, 1
	v_bfe_u32 v66, v65, 16, 1
	v_bfe_u32 v67, v84, 16, 1
	v_bfe_u32 v68, v85, 16, 1
	v_bfe_u32 v12, v87, 16, 1
	v_bfe_u32 v56, v86, 16, 1
	v_add3_u32 v68, v85, v68, s17
	v_add3_u32 v67, v84, v67, s17
	v_add3_u32 v65, v65, v66, s17
	v_add3_u32 v62, v64, v62, s17
	v_add3_u32 v56, v86, v56, s17
	v_add3_u32 v12, v87, v12, s17
	v_lshrrev_b32_e32 v62, 16, v62
	v_lshrrev_b32_e32 v64, 16, v65
	v_lshrrev_b32_e32 v65, 16, v67
	v_lshrrev_b32_e32 v66, 16, v68
	v_and_or_b32 v67, v12, s18, v66
	v_and_or_b32 v66, v56, s18, v65
	v_and_or_b32 v65, v58, s18, v64
	v_and_or_b32 v64, v60, s18, v62
	v_or_b32_e32 v12, s0, v78
	v_mov_b32_e32 v58, v71
	v_mov_b32_e32 v62, v81
	v_addc_co_u32_e32 v83, vcc, 0, v83, vcc
	v_lshlrev_b32_e32 v12, 11, v12
	v_mov_b32_e32 v56, v69
	v_pk_mul_f32 v[36:37], v[36:37], v[58:59]
	v_mov_b32_e32 v60, v73
	v_pk_mul_f32 v[2:3], v[2:3], v[62:63]
	global_store_dwordx4 v[82:83], v[64:67], off nt
	v_pk_mul_f32 v[32:33], v[32:33], v[60:61]
	v_pk_mul_f32 v[4:5], v[4:5], v[62:63]
	v_lshl_add_u64 v[64:65], v[30:31], 0, v[12:13]
	v_pk_mul_f32 v[30:31], v[38:39], v[56:57]
	v_bfe_u32 v12, v3, 16, 1
	v_bfe_u32 v38, v2, 16, 1
	v_bfe_u32 v39, v37, 16, 1
	v_bfe_u32 v66, v36, 16, 1
	v_add3_u32 v36, v36, v66, s17
	v_add3_u32 v37, v37, v39, s17
	v_add3_u32 v2, v2, v38, s17
	v_add3_u32 v3, v3, v12, s17
	v_bfe_u32 v12, v30, 16, 1
	v_bfe_u32 v38, v31, 16, 1
	v_bfe_u32 v39, v32, 16, 1
	v_bfe_u32 v66, v33, 16, 1
	v_add3_u32 v33, v33, v66, s17
	v_add3_u32 v32, v32, v39, s17
	v_add3_u32 v31, v31, v38, s17
	v_add3_u32 v12, v30, v12, s17
	v_lshrrev_b32_e32 v12, 16, v12
	v_lshrrev_b32_e32 v30, 16, v31
	v_lshrrev_b32_e32 v31, 16, v32
	v_lshrrev_b32_e32 v32, 16, v33
	v_and_or_b32 v33, v3, s18, v32
	v_and_or_b32 v32, v2, s18, v31
	v_and_or_b32 v31, v37, s18, v30
	v_and_or_b32 v30, v36, s18, v12
	global_store_dwordx4 v[64:65], v[30:33], off nt
	v_pk_mul_f32 v[2:3], v[6:7], v[56:57]
	v_pk_mul_f32 v[6:7], v[34:35], v[58:59]
	v_pk_mul_f32 v[32:33], v[42:43], v[62:63]
	v_pk_mul_f32 v[30:31], v[40:41], v[60:61]
	v_bfe_u32 v12, v33, 16, 1
	v_bfe_u32 v35, v7, 16, 1
	v_bfe_u32 v34, v32, 16, 1
	v_bfe_u32 v36, v6, 16, 1
	v_add3_u32 v7, v7, v35, s17
	v_add3_u32 v12, v33, v12, s17
	v_bfe_u32 v33, v2, 16, 1
	v_bfe_u32 v35, v30, 16, 1
	v_add3_u32 v6, v6, v36, s17
	v_add3_u32 v32, v32, v34, s17
	v_bfe_u32 v34, v3, 16, 1
	v_bfe_u32 v36, v31, 16, 1
	v_add3_u32 v30, v30, v35, s17
	v_add3_u32 v2, v2, v33, s17
	v_add3_u32 v31, v31, v36, s17
	v_add3_u32 v3, v3, v34, s17
	v_lshrrev_b32_e32 v2, 16, v2
	v_lshrrev_b32_e32 v30, 16, v30
	v_lshrrev_b32_e32 v3, 16, v3
	v_lshrrev_b32_e32 v31, 16, v31
	v_and_or_b32 v32, v32, s18, v30
	v_and_or_b32 v30, v6, s18, v2
	v_add_co_u32_e32 v2, vcc, s19, v64
	v_and_or_b32 v33, v12, s18, v31
	v_and_or_b32 v31, v7, s18, v3
	v_addc_co_u32_e32 v3, vcc, 0, v65, vcc
	global_store_dwordx4 v[2:3], v[30:33], off nt
	v_pk_mul_f32 v[6:7], v[46:47], v[58:59]
	v_pk_mul_f32 v[2:3], v[44:45], v[56:57]
	v_pk_mul_f32 v[32:33], v[50:51], v[62:63]
	v_pk_mul_f32 v[30:31], v[48:49], v[60:61]
	v_bfe_u32 v12, v33, 16, 1
	v_bfe_u32 v35, v7, 16, 1
	v_bfe_u32 v34, v32, 16, 1
	v_bfe_u32 v36, v6, 16, 1
	v_add3_u32 v7, v7, v35, s17
	v_add3_u32 v12, v33, v12, s17
	v_bfe_u32 v33, v2, 16, 1
	v_bfe_u32 v35, v30, 16, 1
	v_add3_u32 v6, v6, v36, s17
	v_add3_u32 v32, v32, v34, s17
	v_bfe_u32 v34, v3, 16, 1
	v_bfe_u32 v36, v31, 16, 1
	v_add3_u32 v30, v30, v35, s17
	v_add3_u32 v2, v2, v33, s17
	v_add3_u32 v31, v31, v36, s17
	v_add3_u32 v3, v3, v34, s17
	v_lshrrev_b32_e32 v2, 16, v2
	v_lshrrev_b32_e32 v30, 16, v30
	v_lshrrev_b32_e32 v3, 16, v3
	v_lshrrev_b32_e32 v31, 16, v31
	v_and_or_b32 v32, v32, s18, v30
	v_and_or_b32 v30, v6, s18, v2
	v_add_co_u32_e32 v2, vcc, s20, v64
	v_and_or_b32 v33, v12, s18, v31
	v_and_or_b32 v31, v7, s18, v3
	v_addc_co_u32_e32 v3, vcc, 0, v65, vcc
	global_store_dwordx4 v[2:3], v[30:33], off nt
	v_pk_mul_f32 v[2:3], v[52:53], v[56:57]
	v_pk_mul_f32 v[6:7], v[8:9], v[58:59]
	v_bfe_u32 v12, v5, 16, 1
	v_pk_mul_f32 v[8:9], v[54:55], v[60:61]
	v_bfe_u32 v30, v4, 16, 1
	v_bfe_u32 v31, v7, 16, 1
	v_bfe_u32 v32, v6, 16, 1
	v_add3_u32 v5, v5, v12, s17
	v_bfe_u32 v12, v2, 16, 1
	v_add3_u32 v6, v6, v32, s17
	v_add3_u32 v7, v7, v31, s17
	v_add3_u32 v4, v4, v30, s17
	v_bfe_u32 v30, v3, 16, 1
	v_bfe_u32 v31, v8, 16, 1
	v_bfe_u32 v32, v9, 16, 1
	v_add3_u32 v2, v2, v12, s17
	v_add3_u32 v9, v9, v32, s17
	v_add3_u32 v8, v8, v31, s17
	v_add3_u32 v3, v3, v30, s17
	v_lshrrev_b32_e32 v2, 16, v2
	v_lshrrev_b32_e32 v3, 16, v3
	v_lshrrev_b32_e32 v8, 16, v8
	v_lshrrev_b32_e32 v9, 16, v9
	v_and_or_b32 v2, v6, s18, v2
	v_add_co_u32_e32 v6, vcc, 0x1800000, v64
	v_and_or_b32 v5, v5, s18, v9
	v_and_or_b32 v4, v4, s18, v8
	v_and_or_b32 v3, v7, s18, v3
	v_addc_co_u32_e32 v7, vcc, 0, v65, vcc
	global_store_dwordx4 v[6:7], v[2:5], off nt
	s_waitcnt lgkmcnt(0)

.LBB0_694:
	s_lshl_b32 s23, s14, 1
	s_lshl_b32 s28, s15, 1
	v_or_b32_e32 v47, s28, v10
	s_add_i32 s29, s23, 4
	s_add_i32 s30, s28, 4
	s_add_i32 s33, s28, 8
	v_add_u32_e32 v12, s13, v47
	v_or_b32_e32 v48, s29, v1
	v_or_b32_e32 v49, s30, v10
	v_mov_b32_e32 v7, v13
	v_or_b32_e32 v46, s23, v1
	s_add_i32 s35, s28, 12
	v_or_b32_e32 v51, s33, v10
	v_lshlrev_b64 v[40:41], 12, v[12:13]
	v_add_u32_e32 v6, s0, v48
	v_add_u32_e32 v12, s13, v49
	v_mov_b32_e32 v5, v13
	s_add_i32 s31, s23, 8
	s_add_i32 s34, s23, 12
	s_add_i32 s37, s28, 16
	v_add_u32_e32 v4, s0, v46
	v_or_b32_e32 v53, s35, v10
	v_lshlrev_b64 v[6:7], 12, v[6:7]
	v_lshlrev_b64 v[42:43], 12, v[12:13]
	v_add_u32_e32 v12, s13, v51
	s_add_i32 s39, s28, 20
	v_or_b32_e32 v50, s31, v1
	v_or_b32_e32 v52, s34, v1
	v_or_b32_e32 v55, s37, v10
	v_lshlrev_b64 v[4:5], 12, v[4:5]
	v_lshl_add_u64 v[40:41], v[2:3], 0, v[40:41]
	v_lshl_add_u64 v[6:7], v[2:3], 0, v[6:7]
	v_lshlrev_b64 v[44:45], 12, v[12:13]
	v_add_u32_e32 v12, s13, v53
	v_mov_b32_e32 v9, v13
	v_mov_b32_e32 v31, v13
	s_add_i32 s36, s23, 16
	s_add_i32 s38, s23, 20
	s_add_i32 s41, s28, 24
	v_or_b32_e32 v57, s39, v10
	v_add_u32_e32 v8, s0, v50
	v_add_u32_e32 v30, s0, v52
	v_lshl_add_u64 v[4:5], v[2:3], 0, v[4:5]
	v_lshl_add_u64 v[42:43], v[2:3], 0, v[42:43]
	global_load_dword v62, v[40:41], off nt
	global_load_dword v63, v[4:5], off nt
	global_load_dword v64, v[42:43], off nt
	global_load_dword v65, v[6:7], off nt
	v_lshlrev_b64 v[6:7], 12, v[12:13]
	v_add_u32_e32 v12, s13, v55
	s_add_i32 s40, s23, 24
	s_add_i32 s23, s23, 28
	s_add_i32 s28, s28, 28
	v_or_b32_e32 v54, s36, v1
	v_or_b32_e32 v56, s38, v1
	v_or_b32_e32 v59, s41, v10
	v_lshlrev_b64 v[8:9], 12, v[8:9]
	v_lshlrev_b64 v[30:31], 12, v[30:31]
	v_lshl_add_u64 v[4:5], v[2:3], 0, v[44:45]
	v_lshl_add_u64 v[6:7], v[2:3], 0, v[6:7]
	v_lshlrev_b64 v[40:41], 12, v[12:13]
	v_add_u32_e32 v12, s13, v57
	v_mov_b32_e32 v33, v13
	v_mov_b32_e32 v35, v13
	v_or_b32_e32 v58, s40, v1
	v_or_b32_e32 v60, s23, v1
	v_or_b32_e32 v61, s28, v10
	v_add_u32_e32 v32, s0, v54
	v_add_u32_e32 v34, s0, v56
	v_lshl_add_u64 v[8:9], v[2:3], 0, v[8:9]
	v_lshl_add_u64 v[30:31], v[2:3], 0, v[30:31]
	global_load_dword v66, v[4:5], off nt
	global_load_dword v67, v[8:9], off nt
	global_load_dword v68, v[6:7], off nt
	global_load_dword v69, v[30:31], off nt
	v_lshlrev_b64 v[6:7], 12, v[12:13]
	v_add_u32_e32 v12, s13, v59
	v_mov_b32_e32 v37, v13
	v_mov_b32_e32 v39, v13
	v_add_u32_e32 v36, s0, v58
	v_add_u32_e32 v38, s0, v60
	v_lshlrev_b64 v[32:33], 12, v[32:33]
	v_lshlrev_b64 v[34:35], 12, v[34:35]
	v_lshl_add_u64 v[4:5], v[2:3], 0, v[40:41]
	v_lshl_add_u64 v[6:7], v[2:3], 0, v[6:7]
	v_lshlrev_b64 v[8:9], 12, v[12:13]
	v_add_u32_e32 v12, s13, v61
	v_lshlrev_b64 v[36:37], 12, v[36:37]
	v_lshlrev_b64 v[38:39], 12, v[38:39]
	v_lshl_add_u64 v[32:33], v[2:3], 0, v[32:33]
	v_lshl_add_u64 v[34:35], v[2:3], 0, v[34:35]
	global_load_dword v70, v[4:5], off nt
	global_load_dword v71, v[32:33], off nt
	global_load_dword v72, v[6:7], off nt
	global_load_dword v73, v[34:35], off nt
	v_lshl_add_u64 v[4:5], v[2:3], 0, v[8:9]
	v_lshlrev_b64 v[6:7], 12, v[12:13]
	v_lshl_add_u64 v[36:37], v[2:3], 0, v[36:37]
	v_lshl_add_u64 v[38:39], v[2:3], 0, v[38:39]
	v_lshl_add_u64 v[6:7], v[2:3], 0, v[6:7]
	global_load_dword v12, v[4:5], off nt
	global_load_dword v79, v[36:37], off nt
	global_load_dword v80, v[6:7], off nt
	global_load_dword v81, v[38:39], off nt
	s_add_i32 s15, s15, 16
	s_add_i32 s14, s14, 16
	s_add_i32 s22, s22, -16
	v_mad_u64_u32 v[4:5], s[28:29], v47, s3, v[16:17]
	s_cmp_lg_u32 s22, 0
	v_mad_u64_u32 v[6:7], s[28:29], v46, s3, v[16:17]
	v_mad_u64_u32 v[8:9], s[28:29], v49, s3, v[16:17]
	v_mad_u64_u32 v[30:31], s[28:29], v48, s3, v[16:17]
	v_mad_u64_u32 v[32:33], s[28:29], v51, s3, v[16:17]
	v_mad_u64_u32 v[34:35], s[28:29], v50, s3, v[16:17]
	v_mad_u64_u32 v[36:37], s[28:29], v53, s3, v[16:17]
	v_mad_u64_u32 v[38:39], s[28:29], v52, s3, v[16:17]
	v_mad_u64_u32 v[40:41], s[28:29], v55, s3, v[16:17]
	v_mad_u64_u32 v[42:43], s[28:29], v54, s3, v[16:17]
	v_mad_u64_u32 v[44:45], s[28:29], v57, s3, v[16:17]
	v_mad_u64_u32 v[46:47], s[28:29], v56, s3, v[16:17]
	v_mad_u64_u32 v[48:49], s[28:29], v59, s3, v[16:17]
	v_mad_u64_u32 v[50:51], s[28:29], v58, s3, v[16:17]
	v_mad_u64_u32 v[52:53], s[28:29], v61, s3, v[16:17]
	v_mad_u64_u32 v[54:55], s[28:29], v60, s3, v[16:17]
	s_waitcnt vmcnt(15)
	ds_write_b32 v4, v62
	s_waitcnt vmcnt(14)
	ds_write_b32 v6, v63
	s_waitcnt vmcnt(13)
	ds_write_b32 v8, v64
	s_waitcnt vmcnt(12)
	ds_write_b32 v30, v65
	s_waitcnt vmcnt(11)
	ds_write_b32 v32, v66
	s_waitcnt vmcnt(10)
	ds_write_b32 v34, v67
	s_waitcnt vmcnt(9)
	ds_write_b32 v36, v68
	s_waitcnt vmcnt(8)
	ds_write_b32 v38, v69
	s_waitcnt vmcnt(7)
	ds_write_b32 v40, v70
	s_waitcnt vmcnt(6)
	ds_write_b32 v42, v71
	s_waitcnt vmcnt(5)
	ds_write_b32 v44, v72
	s_waitcnt vmcnt(4)
	ds_write_b32 v46, v73
	s_waitcnt vmcnt(3)
	ds_write_b32 v48, v12
	s_waitcnt vmcnt(2)
	ds_write_b32 v50, v79
	s_waitcnt vmcnt(1)
	ds_write_b32 v52, v80
	s_waitcnt vmcnt(0)
	ds_write_b32 v54, v81
	s_cbranch_scc1 .LBB0_694
	s_waitcnt lgkmcnt(0)
	ds_read2_b32 v[6:7], v17 offset1:8
	ds_read2_b32 v[30:31], v17 offset0:33 offset1:41
	ds_read2_b32 v[32:33], v17 offset0:66 offset1:74
	ds_read2_b32 v[34:35], v17 offset0:99 offset1:107
	ds_read2_b32 v[36:37], v17 offset0:132 offset1:140
	ds_read2_b32 v[38:39], v17 offset0:165 offset1:173
	s_waitcnt lgkmcnt(5)
	v_bfe_u32 v2, v6, 16, 1
	v_add3_u32 v2, v6, v2, s17
	s_waitcnt lgkmcnt(4)
	v_bfe_u32 v3, v30, 16, 1
	v_lshrrev_b32_e32 v2, 16, v2
	v_add3_u32 v3, v30, v3, s17
	v_and_or_b32 v2, v3, s18, v2
	s_waitcnt lgkmcnt(3)
	v_bfe_u32 v3, v32, 16, 1
	v_add3_u32 v3, v32, v3, s17
	s_waitcnt lgkmcnt(2)
	v_bfe_u32 v4, v34, 16, 1
	ds_read2_b32 v[40:41], v17 offset0:198 offset1:206
	v_lshrrev_b32_e32 v3, 16, v3
	v_add3_u32 v4, v34, v4, s17
	ds_read2_b32 v[42:43], v17 offset0:231 offset1:239
	v_and_or_b32 v3, v4, s18, v3
	s_waitcnt lgkmcnt(3)
	v_bfe_u32 v4, v36, 16, 1
	v_add3_u32 v4, v36, v4, s17
	s_waitcnt lgkmcnt(2)
	v_bfe_u32 v5, v38, 16, 1
	v_lshrrev_b32_e32 v4, 16, v4
	v_add3_u32 v5, v38, v5, s17
	v_and_or_b32 v4, v5, s18, v4
	s_waitcnt lgkmcnt(1)
	v_bfe_u32 v5, v40, 16, 1
	v_add3_u32 v5, v40, v5, s17
	s_waitcnt lgkmcnt(0)
	v_bfe_u32 v6, v42, 16, 1
	v_lshrrev_b32_e32 v5, 16, v5
	v_add3_u32 v6, v42, v6, s17
	s_lshl_b32 s0, s13, 1
	v_and_or_b32 v5, v6, s18, v5
	v_or_b32_e32 v6, s12, v74
	v_lshl_add_u64 v[8:9], v[22:23], 0, s[0:1]
	v_lshlrev_b32_e32 v12, 11, v6
	v_lshl_add_u64 v[44:45], v[8:9], 0, v[12:13]
	global_store_dwordx4 v[44:45], v[2:5], off nt
	v_bfe_u32 v6, v43, 16, 1
	v_or_b32_e32 v12, s12, v76
	v_bfe_u32 v2, v7, 16, 1
	v_add3_u32 v2, v7, v2, s17
	v_bfe_u32 v3, v31, 16, 1
	v_lshrrev_b32_e32 v2, 16, v2
	v_add3_u32 v3, v31, v3, s17
	v_and_or_b32 v2, v3, s18, v2
	v_bfe_u32 v3, v33, 16, 1
	v_add3_u32 v3, v33, v3, s17
	v_bfe_u32 v4, v35, 16, 1
	v_lshrrev_b32_e32 v3, 16, v3
	v_add3_u32 v4, v35, v4, s17
	v_and_or_b32 v3, v4, s18, v3
	v_bfe_u32 v4, v37, 16, 1
	v_add3_u32 v4, v37, v4, s17
	v_bfe_u32 v5, v39, 16, 1
	v_lshrrev_b32_e32 v4, 16, v4
	v_add3_u32 v5, v39, v5, s17
	v_and_or_b32 v4, v5, s18, v4
	v_bfe_u32 v5, v41, 16, 1
	v_add3_u32 v5, v41, v5, s17
	v_lshrrev_b32_e32 v5, 16, v5
	v_add3_u32 v6, v43, v6, s17
	v_lshlrev_b32_e32 v12, 11, v12
	v_and_or_b32 v5, v6, s18, v5
	ds_read2_b32 v[6:7], v17 offset0:16 offset1:24
	v_lshl_add_u64 v[30:31], v[8:9], 0, v[12:13]
	global_store_dwordx4 v[30:31], v[2:5], off nt
	ds_read2_b32 v[30:31], v17 offset0:49 offset1:57
	ds_read2_b32 v[32:33], v17 offset0:82 offset1:90
	ds_read2_b32 v[34:35], v17 offset0:115 offset1:123
	s_waitcnt lgkmcnt(3)
	v_bfe_u32 v2, v6, 16, 1
	v_add3_u32 v2, v6, v2, s17
	s_waitcnt lgkmcnt(2)
	v_bfe_u32 v3, v30, 16, 1
	ds_read2_b32 v[36:37], v17 offset0:148 offset1:156
	v_lshrrev_b32_e32 v2, 16, v2
	v_add3_u32 v3, v30, v3, s17
	ds_read2_b32 v[38:39], v17 offset0:181 offset1:189
	v_and_or_b32 v2, v3, s18, v2
	s_waitcnt lgkmcnt(3)
	v_bfe_u32 v3, v32, 16, 1
	v_add3_u32 v3, v32, v3, s17
	s_waitcnt lgkmcnt(2)
	v_bfe_u32 v4, v34, 16, 1
	ds_read2_b32 v[40:41], v17 offset0:214 offset1:222
	v_lshrrev_b32_e32 v3, 16, v3
	v_add3_u32 v4, v34, v4, s17
	ds_read2_b32 v[42:43], v17 offset0:247 offset1:255
	v_and_or_b32 v3, v4, s18, v3
	s_waitcnt lgkmcnt(3)
	v_bfe_u32 v4, v36, 16, 1
	v_add3_u32 v4, v36, v4, s17
	s_waitcnt lgkmcnt(2)
	v_bfe_u32 v5, v38, 16, 1
	v_lshrrev_b32_e32 v4, 16, v4
	v_add3_u32 v5, v38, v5, s17
	v_and_or_b32 v4, v5, s18, v4
	s_waitcnt lgkmcnt(1)
	v_bfe_u32 v5, v40, 16, 1
	v_add3_u32 v5, v40, v5, s17
	s_waitcnt lgkmcnt(0)
	v_bfe_u32 v6, v42, 16, 1
	v_lshrrev_b32_e32 v5, 16, v5
	v_add3_u32 v6, v42, v6, s17
	v_and_or_b32 v5, v6, s18, v5
	v_or_b32_e32 v6, s12, v77
	v_lshlrev_b32_e32 v12, 11, v6
	v_lshl_add_u64 v[44:45], v[8:9], 0, v[12:13]
	global_store_dwordx4 v[44:45], v[2:5], off nt
	v_bfe_u32 v6, v43, 16, 1
	v_add3_u32 v6, v43, v6, s17
	v_bfe_u32 v2, v7, 16, 1
	v_add3_u32 v2, v7, v2, s17
	v_bfe_u32 v3, v31, 16, 1
	v_lshrrev_b32_e32 v2, 16, v2
	v_add3_u32 v3, v31, v3, s17
	v_and_or_b32 v2, v3, s18, v2
	v_bfe_u32 v3, v33, 16, 1
	v_add3_u32 v3, v33, v3, s17
	v_bfe_u32 v4, v35, 16, 1
	v_lshrrev_b32_e32 v3, 16, v3
	v_add3_u32 v4, v35, v4, s17
	v_and_or_b32 v3, v4, s18, v3
	v_bfe_u32 v4, v37, 16, 1
	v_add3_u32 v4, v37, v4, s17
	v_bfe_u32 v5, v39, 16, 1
	v_lshrrev_b32_e32 v4, 16, v4
	v_add3_u32 v5, v39, v5, s17
	v_and_or_b32 v4, v5, s18, v4
	v_bfe_u32 v5, v41, 16, 1
	v_add3_u32 v5, v41, v5, s17
	v_lshrrev_b32_e32 v5, 16, v5
	v_and_or_b32 v5, v6, s18, v5
	v_or_b32_e32 v6, s12, v78
	v_lshlrev_b32_e32 v12, 11, v6
	v_lshl_add_u64 v[6:7], v[8:9], 0, v[12:13]
	global_store_dwordx4 v[6:7], v[2:5], off nt
	s_waitcnt lgkmcnt(0)

.LBB0_699:
	s_lshl_b32 s23, s14, 1
	s_lshl_b32 s28, s15, 1
	v_or_b32_e32 v47, s28, v10
	s_add_i32 s29, s23, 4
	s_add_i32 s30, s28, 4
	s_add_i32 s33, s28, 8
	v_add_u32_e32 v12, s13, v47
	v_or_b32_e32 v48, s29, v1
	v_or_b32_e32 v49, s30, v10
	v_mov_b32_e32 v7, v13
	v_or_b32_e32 v46, s23, v1
	s_add_i32 s35, s28, 12
	v_or_b32_e32 v51, s33, v10
	v_lshlrev_b64 v[40:41], 12, v[12:13]
	v_add_u32_e32 v6, s0, v48
	v_add_u32_e32 v12, s13, v49
	v_mov_b32_e32 v5, v13
	s_add_i32 s31, s23, 8
	s_add_i32 s34, s23, 12
	s_add_i32 s37, s28, 16
	v_add_u32_e32 v4, s0, v46
	v_or_b32_e32 v53, s35, v10
	v_lshlrev_b64 v[6:7], 12, v[6:7]
	v_lshlrev_b64 v[42:43], 12, v[12:13]
	v_add_u32_e32 v12, s13, v51
	s_add_i32 s39, s28, 20
	v_or_b32_e32 v50, s31, v1
	v_or_b32_e32 v52, s34, v1
	v_or_b32_e32 v55, s37, v10
	v_lshlrev_b64 v[4:5], 12, v[4:5]
	v_lshl_add_u64 v[40:41], v[2:3], 0, v[40:41]
	v_lshl_add_u64 v[6:7], v[2:3], 0, v[6:7]
	v_lshlrev_b64 v[44:45], 12, v[12:13]
	v_add_u32_e32 v12, s13, v53
	v_mov_b32_e32 v9, v13
	v_mov_b32_e32 v31, v13
	s_add_i32 s36, s23, 16
	s_add_i32 s38, s23, 20
	s_add_i32 s41, s28, 24
	v_or_b32_e32 v57, s39, v10
	v_add_u32_e32 v8, s0, v50
	v_add_u32_e32 v30, s0, v52
	v_lshl_add_u64 v[4:5], v[2:3], 0, v[4:5]
	v_lshl_add_u64 v[42:43], v[2:3], 0, v[42:43]
	global_load_dword v62, v[40:41], off nt
	global_load_dword v63, v[4:5], off nt
	global_load_dword v64, v[42:43], off nt
	global_load_dword v65, v[6:7], off nt
	v_lshlrev_b64 v[6:7], 12, v[12:13]
	v_add_u32_e32 v12, s13, v55
	s_add_i32 s40, s23, 24
	s_add_i32 s23, s23, 28
	s_add_i32 s28, s28, 28
	v_or_b32_e32 v54, s36, v1
	v_or_b32_e32 v56, s38, v1
	v_or_b32_e32 v59, s41, v10
	v_lshlrev_b64 v[8:9], 12, v[8:9]
	v_lshlrev_b64 v[30:31], 12, v[30:31]
	v_lshl_add_u64 v[4:5], v[2:3], 0, v[44:45]
	v_lshl_add_u64 v[6:7], v[2:3], 0, v[6:7]
	v_lshlrev_b64 v[40:41], 12, v[12:13]
	v_add_u32_e32 v12, s13, v57
	v_mov_b32_e32 v33, v13
	v_mov_b32_e32 v35, v13
	v_or_b32_e32 v58, s40, v1
	v_or_b32_e32 v60, s23, v1
	v_or_b32_e32 v61, s28, v10
	v_add_u32_e32 v32, s0, v54
	v_add_u32_e32 v34, s0, v56
	v_lshl_add_u64 v[8:9], v[2:3], 0, v[8:9]
	v_lshl_add_u64 v[30:31], v[2:3], 0, v[30:31]
	global_load_dword v66, v[4:5], off nt
	global_load_dword v67, v[8:9], off nt
	global_load_dword v68, v[6:7], off nt
	global_load_dword v69, v[30:31], off nt
	v_lshlrev_b64 v[6:7], 12, v[12:13]
	v_add_u32_e32 v12, s13, v59
	v_mov_b32_e32 v37, v13
	v_mov_b32_e32 v39, v13
	v_add_u32_e32 v36, s0, v58
	v_add_u32_e32 v38, s0, v60
	v_lshlrev_b64 v[32:33], 12, v[32:33]
	v_lshlrev_b64 v[34:35], 12, v[34:35]
	v_lshl_add_u64 v[4:5], v[2:3], 0, v[40:41]
	v_lshl_add_u64 v[6:7], v[2:3], 0, v[6:7]
	v_lshlrev_b64 v[8:9], 12, v[12:13]
	v_add_u32_e32 v12, s13, v61
	v_lshlrev_b64 v[36:37], 12, v[36:37]
	v_lshlrev_b64 v[38:39], 12, v[38:39]
	v_lshl_add_u64 v[32:33], v[2:3], 0, v[32:33]
	v_lshl_add_u64 v[34:35], v[2:3], 0, v[34:35]
	global_load_dword v70, v[4:5], off nt
	global_load_dword v71, v[32:33], off nt
	global_load_dword v72, v[6:7], off nt
	global_load_dword v73, v[34:35], off nt
	v_lshl_add_u64 v[4:5], v[2:3], 0, v[8:9]
	v_lshlrev_b64 v[6:7], 12, v[12:13]
	v_lshl_add_u64 v[36:37], v[2:3], 0, v[36:37]
	v_lshl_add_u64 v[38:39], v[2:3], 0, v[38:39]
	v_lshl_add_u64 v[6:7], v[2:3], 0, v[6:7]
	global_load_dword v12, v[4:5], off nt
	global_load_dword v79, v[36:37], off nt
	global_load_dword v80, v[6:7], off nt
	global_load_dword v81, v[38:39], off nt
	s_add_i32 s15, s15, 16
	s_add_i32 s14, s14, 16
	s_add_i32 s22, s22, -16
	v_mad_u64_u32 v[4:5], s[28:29], v47, s3, v[16:17]
	s_cmp_lg_u32 s22, 0
	v_mad_u64_u32 v[6:7], s[28:29], v46, s3, v[16:17]
	v_mad_u64_u32 v[8:9], s[28:29], v49, s3, v[16:17]
	v_mad_u64_u32 v[30:31], s[28:29], v48, s3, v[16:17]
	v_mad_u64_u32 v[32:33], s[28:29], v51, s3, v[16:17]
	v_mad_u64_u32 v[34:35], s[28:29], v50, s3, v[16:17]
	v_mad_u64_u32 v[36:37], s[28:29], v53, s3, v[16:17]
	v_mad_u64_u32 v[38:39], s[28:29], v52, s3, v[16:17]
	v_mad_u64_u32 v[40:41], s[28:29], v55, s3, v[16:17]
	v_mad_u64_u32 v[42:43], s[28:29], v54, s3, v[16:17]
	v_mad_u64_u32 v[44:45], s[28:29], v57, s3, v[16:17]
	v_mad_u64_u32 v[46:47], s[28:29], v56, s3, v[16:17]
	v_mad_u64_u32 v[48:49], s[28:29], v59, s3, v[16:17]
	v_mad_u64_u32 v[50:51], s[28:29], v58, s3, v[16:17]
	v_mad_u64_u32 v[52:53], s[28:29], v61, s3, v[16:17]
	v_mad_u64_u32 v[54:55], s[28:29], v60, s3, v[16:17]
	s_waitcnt vmcnt(15)
	ds_write_b32 v4, v62
	s_waitcnt vmcnt(14)
	ds_write_b32 v6, v63
	s_waitcnt vmcnt(13)
	ds_write_b32 v8, v64
	s_waitcnt vmcnt(12)
	ds_write_b32 v30, v65
	s_waitcnt vmcnt(11)
	ds_write_b32 v32, v66
	s_waitcnt vmcnt(10)
	ds_write_b32 v34, v67
	s_waitcnt vmcnt(9)
	ds_write_b32 v36, v68
	s_waitcnt vmcnt(8)
	ds_write_b32 v38, v69
	s_waitcnt vmcnt(7)
	ds_write_b32 v40, v70
	s_waitcnt vmcnt(6)
	ds_write_b32 v42, v71
	s_waitcnt vmcnt(5)
	ds_write_b32 v44, v72
	s_waitcnt vmcnt(4)
	ds_write_b32 v46, v73
	s_waitcnt vmcnt(3)
	ds_write_b32 v48, v12
	s_waitcnt vmcnt(2)
	ds_write_b32 v50, v79
	s_waitcnt vmcnt(1)
	ds_write_b32 v52, v80
	s_waitcnt vmcnt(0)
	ds_write_b32 v54, v81
	s_cbranch_scc1 .LBB0_699
	s_waitcnt lgkmcnt(0)
	ds_read2_b32 v[6:7], v17 offset1:8
	ds_read2_b32 v[30:31], v17 offset0:33 offset1:41
	ds_read2_b32 v[32:33], v17 offset0:66 offset1:74
	ds_read2_b32 v[34:35], v17 offset0:99 offset1:107
	ds_read2_b32 v[36:37], v17 offset0:132 offset1:140
	ds_read2_b32 v[38:39], v17 offset0:165 offset1:173
	s_waitcnt lgkmcnt(5)
	v_bfe_u32 v2, v6, 16, 1
	v_add3_u32 v2, v6, v2, s17
	s_waitcnt lgkmcnt(4)
	v_bfe_u32 v3, v30, 16, 1
	v_lshrrev_b32_e32 v2, 16, v2
	v_add3_u32 v3, v30, v3, s17
	v_and_or_b32 v2, v3, s18, v2
	s_waitcnt lgkmcnt(3)
	v_bfe_u32 v3, v32, 16, 1
	v_add3_u32 v3, v32, v3, s17
	s_waitcnt lgkmcnt(2)
	v_bfe_u32 v4, v34, 16, 1
	ds_read2_b32 v[40:41], v17 offset0:198 offset1:206
	v_lshrrev_b32_e32 v3, 16, v3
	v_add3_u32 v4, v34, v4, s17
	ds_read2_b32 v[42:43], v17 offset0:231 offset1:239
	v_and_or_b32 v3, v4, s18, v3
	s_waitcnt lgkmcnt(3)
	v_bfe_u32 v4, v36, 16, 1
	v_add3_u32 v4, v36, v4, s17
	s_waitcnt lgkmcnt(2)
	v_bfe_u32 v5, v38, 16, 1
	v_lshrrev_b32_e32 v4, 16, v4
	v_add3_u32 v5, v38, v5, s17
	v_and_or_b32 v4, v5, s18, v4
	s_waitcnt lgkmcnt(1)
	v_bfe_u32 v5, v40, 16, 1
	v_add3_u32 v5, v40, v5, s17
	s_waitcnt lgkmcnt(0)
	v_bfe_u32 v6, v42, 16, 1
	v_lshrrev_b32_e32 v5, 16, v5
	v_add3_u32 v6, v42, v6, s17
	s_lshl_b32 s0, s13, 1
	v_and_or_b32 v5, v6, s18, v5
	v_or_b32_e32 v6, s12, v74
	v_lshl_add_u64 v[8:9], v[28:29], 0, s[0:1]
	v_lshlrev_b32_e32 v12, 11, v6
	v_lshl_add_u64 v[44:45], v[8:9], 0, v[12:13]
	global_store_dwordx4 v[44:45], v[2:5], off offset:1024 nt
	v_bfe_u32 v6, v43, 16, 1
	v_or_b32_e32 v12, s12, v76
	v_bfe_u32 v2, v7, 16, 1
	v_add3_u32 v2, v7, v2, s17
	v_bfe_u32 v3, v31, 16, 1
	v_lshrrev_b32_e32 v2, 16, v2
	v_add3_u32 v3, v31, v3, s17
	v_and_or_b32 v2, v3, s18, v2
	v_bfe_u32 v3, v33, 16, 1
	v_add3_u32 v3, v33, v3, s17
	v_bfe_u32 v4, v35, 16, 1
	v_lshrrev_b32_e32 v3, 16, v3
	v_add3_u32 v4, v35, v4, s17
	v_and_or_b32 v3, v4, s18, v3
	v_bfe_u32 v4, v37, 16, 1
	v_add3_u32 v4, v37, v4, s17
	v_bfe_u32 v5, v39, 16, 1
	v_lshrrev_b32_e32 v4, 16, v4
	v_add3_u32 v5, v39, v5, s17
	v_and_or_b32 v4, v5, s18, v4
	v_bfe_u32 v5, v41, 16, 1
	v_add3_u32 v5, v41, v5, s17
	v_lshrrev_b32_e32 v5, 16, v5
	v_add3_u32 v6, v43, v6, s17
	v_lshlrev_b32_e32 v12, 11, v12
	v_and_or_b32 v5, v6, s18, v5
	ds_read2_b32 v[6:7], v17 offset0:16 offset1:24
	v_lshl_add_u64 v[30:31], v[8:9], 0, v[12:13]
	global_store_dwordx4 v[30:31], v[2:5], off offset:1024 nt
	ds_read2_b32 v[30:31], v17 offset0:49 offset1:57
	ds_read2_b32 v[32:33], v17 offset0:82 offset1:90
	ds_read2_b32 v[34:35], v17 offset0:115 offset1:123
	s_waitcnt lgkmcnt(3)
	v_bfe_u32 v2, v6, 16, 1
	v_add3_u32 v2, v6, v2, s17
	s_waitcnt lgkmcnt(2)
	v_bfe_u32 v3, v30, 16, 1
	ds_read2_b32 v[36:37], v17 offset0:148 offset1:156
	v_lshrrev_b32_e32 v2, 16, v2
	v_add3_u32 v3, v30, v3, s17
	ds_read2_b32 v[38:39], v17 offset0:181 offset1:189
	v_and_or_b32 v2, v3, s18, v2
	s_waitcnt lgkmcnt(3)
	v_bfe_u32 v3, v32, 16, 1
	v_add3_u32 v3, v32, v3, s17
	s_waitcnt lgkmcnt(2)
	v_bfe_u32 v4, v34, 16, 1
	ds_read2_b32 v[40:41], v17 offset0:214 offset1:222
	v_lshrrev_b32_e32 v3, 16, v3
	v_add3_u32 v4, v34, v4, s17
	ds_read2_b32 v[42:43], v17 offset0:247 offset1:255
	v_and_or_b32 v3, v4, s18, v3
	s_waitcnt lgkmcnt(3)
	v_bfe_u32 v4, v36, 16, 1
	v_add3_u32 v4, v36, v4, s17
	s_waitcnt lgkmcnt(2)
	v_bfe_u32 v5, v38, 16, 1
	v_lshrrev_b32_e32 v4, 16, v4
	v_add3_u32 v5, v38, v5, s17
	v_and_or_b32 v4, v5, s18, v4
	s_waitcnt lgkmcnt(1)
	v_bfe_u32 v5, v40, 16, 1
	v_add3_u32 v5, v40, v5, s17
	s_waitcnt lgkmcnt(0)
	v_bfe_u32 v6, v42, 16, 1
	v_lshrrev_b32_e32 v5, 16, v5
	v_add3_u32 v6, v42, v6, s17
	v_and_or_b32 v5, v6, s18, v5
	v_or_b32_e32 v6, s12, v77
	v_lshlrev_b32_e32 v12, 11, v6
	v_lshl_add_u64 v[44:45], v[8:9], 0, v[12:13]
	global_store_dwordx4 v[44:45], v[2:5], off offset:1024 nt
	v_bfe_u32 v6, v43, 16, 1
	v_add3_u32 v6, v43, v6, s17
	v_bfe_u32 v2, v7, 16, 1
	v_add3_u32 v2, v7, v2, s17
	v_bfe_u32 v3, v31, 16, 1
	v_lshrrev_b32_e32 v2, 16, v2
	v_add3_u32 v3, v31, v3, s17
	v_and_or_b32 v2, v3, s18, v2
	v_bfe_u32 v3, v33, 16, 1
	v_add3_u32 v3, v33, v3, s17
	v_bfe_u32 v4, v35, 16, 1
	v_lshrrev_b32_e32 v3, 16, v3
	v_add3_u32 v4, v35, v4, s17
	v_and_or_b32 v3, v4, s18, v3
	v_bfe_u32 v4, v37, 16, 1
	v_add3_u32 v4, v37, v4, s17
	v_bfe_u32 v5, v39, 16, 1
	v_lshrrev_b32_e32 v4, 16, v4
	v_add3_u32 v5, v39, v5, s17
	v_and_or_b32 v4, v5, s18, v4
	v_bfe_u32 v5, v41, 16, 1
	v_add3_u32 v5, v41, v5, s17
	v_lshrrev_b32_e32 v5, 16, v5
	v_and_or_b32 v5, v6, s18, v5
	v_or_b32_e32 v6, s12, v78
	v_lshlrev_b32_e32 v12, 11, v6
	v_lshl_add_u64 v[6:7], v[8:9], 0, v[12:13]
	global_store_dwordx4 v[6:7], v[2:5], off offset:1024 nt
	s_waitcnt lgkmcnt(0)

.LBB0_704:
	s_lshl_b32 s23, s0, 1
	s_lshl_b32 s28, s15, 1
	v_or_b32_e32 v12, s23, v1
	v_or_b32_e32 v56, s28, v10
	s_add_i32 s29, s23, 4
	s_add_i32 s30, s28, 4
	s_add_i32 s31, s23, 8
	s_add_i32 s33, s28, 8
	s_add_i32 s34, s23, 12
	s_add_i32 s35, s28, 12
	s_add_i32 s36, s23, 16
	s_add_i32 s37, s28, 16
	s_add_i32 s38, s23, 20
	s_add_i32 s39, s28, 20
	s_add_i32 s40, s23, 24
	s_add_i32 s41, s28, 24
	s_add_i32 s23, s23, 28
	s_add_i32 s28, s28, 28
	v_add_u32_e32 v6, s14, v56
	v_or_b32_e32 v57, s29, v1
	v_or_b32_e32 v58, s30, v10
	v_or_b32_e32 v59, s31, v1
	v_or_b32_e32 v60, s33, v10
	v_or_b32_e32 v61, s34, v1
	v_or_b32_e32 v62, s35, v10
	v_or_b32_e32 v63, s36, v1
	v_or_b32_e32 v64, s37, v10
	v_or_b32_e32 v65, s38, v1
	v_or_b32_e32 v66, s39, v10
	v_or_b32_e32 v67, s40, v1
	v_or_b32_e32 v68, s41, v10
	v_or_b32_e32 v69, s23, v1
	v_or_b32_e32 v70, s28, v10
	v_add_u32_e32 v4, s13, v12
	v_ashrrev_i32_e32 v7, 31, v6
	v_add_u32_e32 v8, s13, v57
	v_add_u32_e32 v30, s14, v58
	v_add_u32_e32 v32, s13, v59
	v_add_u32_e32 v34, s14, v60
	v_add_u32_e32 v36, s13, v61
	v_add_u32_e32 v38, s14, v62
	v_add_u32_e32 v40, s13, v63
	v_add_u32_e32 v42, s14, v64
	v_add_u32_e32 v44, s13, v65
	v_add_u32_e32 v46, s14, v66
	v_add_u32_e32 v48, s13, v67
	v_add_u32_e32 v50, s14, v68
	v_add_u32_e32 v52, s13, v69
	v_add_u32_e32 v54, s14, v70
	v_ashrrev_i32_e32 v5, 31, v4
	v_lshlrev_b64 v[6:7], 12, v[6:7]
	v_ashrrev_i32_e32 v31, 31, v30
	v_ashrrev_i32_e32 v9, 31, v8
	v_ashrrev_i32_e32 v35, 31, v34
	v_ashrrev_i32_e32 v33, 31, v32
	v_ashrrev_i32_e32 v39, 31, v38
	v_ashrrev_i32_e32 v37, 31, v36
	v_ashrrev_i32_e32 v43, 31, v42
	v_ashrrev_i32_e32 v41, 31, v40
	v_ashrrev_i32_e32 v47, 31, v46
	v_ashrrev_i32_e32 v45, 31, v44
	v_ashrrev_i32_e32 v51, 31, v50
	v_ashrrev_i32_e32 v49, 31, v48
	v_ashrrev_i32_e32 v55, 31, v54
	v_ashrrev_i32_e32 v53, 31, v52
	v_lshlrev_b64 v[4:5], 12, v[4:5]
	v_lshl_add_u64 v[6:7], v[2:3], 0, v[6:7]
	v_lshlrev_b64 v[8:9], 12, v[8:9]
	v_lshlrev_b64 v[30:31], 12, v[30:31]
	v_lshlrev_b64 v[32:33], 12, v[32:33]
	v_lshlrev_b64 v[34:35], 12, v[34:35]
	v_lshlrev_b64 v[36:37], 12, v[36:37]
	v_lshlrev_b64 v[38:39], 12, v[38:39]
	v_lshlrev_b64 v[40:41], 12, v[40:41]
	v_lshlrev_b64 v[42:43], 12, v[42:43]
	v_lshlrev_b64 v[44:45], 12, v[44:45]
	v_lshlrev_b64 v[46:47], 12, v[46:47]
	v_lshlrev_b64 v[48:49], 12, v[48:49]
	v_lshlrev_b64 v[50:51], 12, v[50:51]
	v_lshlrev_b64 v[52:53], 12, v[52:53]
	v_lshlrev_b64 v[54:55], 12, v[54:55]
	v_lshl_add_u64 v[4:5], v[2:3], 0, v[4:5]
	v_lshl_add_u64 v[30:31], v[2:3], 0, v[30:31]
	v_lshl_add_u64 v[8:9], v[2:3], 0, v[8:9]
	v_lshl_add_u64 v[34:35], v[2:3], 0, v[34:35]
	v_lshl_add_u64 v[32:33], v[2:3], 0, v[32:33]
	v_lshl_add_u64 v[38:39], v[2:3], 0, v[38:39]
	v_lshl_add_u64 v[36:37], v[2:3], 0, v[36:37]
	v_lshl_add_u64 v[42:43], v[2:3], 0, v[42:43]
	v_lshl_add_u64 v[40:41], v[2:3], 0, v[40:41]
	v_lshl_add_u64 v[46:47], v[2:3], 0, v[46:47]
	v_lshl_add_u64 v[44:45], v[2:3], 0, v[44:45]
	v_lshl_add_u64 v[50:51], v[2:3], 0, v[50:51]
	v_lshl_add_u64 v[48:49], v[2:3], 0, v[48:49]
	v_lshl_add_u64 v[54:55], v[2:3], 0, v[54:55]
	v_lshl_add_u64 v[52:53], v[2:3], 0, v[52:53]
	global_load_dword v71, v[6:7], off nt
	global_load_dword v72, v[4:5], off nt
	global_load_dword v73, v[30:31], off nt
	global_load_dword v79, v[8:9], off nt
	global_load_dword v80, v[34:35], off nt
	global_load_dword v81, v[32:33], off nt
	global_load_dword v82, v[38:39], off nt
	global_load_dword v83, v[36:37], off nt
	global_load_dword v84, v[42:43], off nt
	global_load_dword v85, v[40:41], off nt
	global_load_dword v86, v[46:47], off nt
	global_load_dword v87, v[44:45], off nt
	global_load_dword v88, v[50:51], off nt
	global_load_dword v89, v[48:49], off nt
	global_load_dword v90, v[54:55], off nt
	global_load_dword v91, v[52:53], off nt
	s_add_i32 s15, s15, 16
	s_add_i32 s0, s0, 16
	s_add_i32 s22, s22, -16
	v_mad_u64_u32 v[4:5], s[28:29], v56, s3, v[16:17]
	s_cmp_lg_u32 s22, 0
	v_mad_u64_u32 v[6:7], s[28:29], v12, s3, v[16:17]
	v_mad_u64_u32 v[8:9], s[28:29], v58, s3, v[16:17]
	v_mad_u64_u32 v[30:31], s[28:29], v57, s3, v[16:17]
	v_mad_u64_u32 v[32:33], s[28:29], v60, s3, v[16:17]
	v_mad_u64_u32 v[34:35], s[28:29], v59, s3, v[16:17]
	v_mad_u64_u32 v[36:37], s[28:29], v62, s3, v[16:17]
	v_mad_u64_u32 v[38:39], s[28:29], v61, s3, v[16:17]
	v_mad_u64_u32 v[40:41], s[28:29], v64, s3, v[16:17]
	v_mad_u64_u32 v[42:43], s[28:29], v63, s3, v[16:17]
	v_mad_u64_u32 v[44:45], s[28:29], v66, s3, v[16:17]
	v_mad_u64_u32 v[46:47], s[28:29], v65, s3, v[16:17]
	v_mad_u64_u32 v[48:49], s[28:29], v68, s3, v[16:17]
	v_mad_u64_u32 v[50:51], s[28:29], v67, s3, v[16:17]
	v_mad_u64_u32 v[52:53], s[28:29], v70, s3, v[16:17]
	v_mad_u64_u32 v[54:55], s[28:29], v69, s3, v[16:17]
	s_waitcnt vmcnt(15)
	ds_write_b32 v4, v71
	s_waitcnt vmcnt(14)
	ds_write_b32 v6, v72
	s_waitcnt vmcnt(13)
	ds_write_b32 v8, v73
	s_waitcnt vmcnt(12)
	ds_write_b32 v30, v79
	s_waitcnt vmcnt(11)
	ds_write_b32 v32, v80
	s_waitcnt vmcnt(10)
	ds_write_b32 v34, v81
	s_waitcnt vmcnt(9)
	ds_write_b32 v36, v82
	s_waitcnt vmcnt(8)
	ds_write_b32 v38, v83
	s_waitcnt vmcnt(7)
	ds_write_b32 v40, v84
	s_waitcnt vmcnt(6)
	ds_write_b32 v42, v85
	s_waitcnt vmcnt(5)
	ds_write_b32 v44, v86
	s_waitcnt vmcnt(4)
	ds_write_b32 v46, v87
	s_waitcnt vmcnt(3)
	ds_write_b32 v48, v88
	s_waitcnt vmcnt(2)
	ds_write_b32 v50, v89
	s_waitcnt vmcnt(1)
	ds_write_b32 v52, v90
	s_waitcnt vmcnt(0)
	ds_write_b32 v54, v91
	s_cbranch_scc1 .LBB0_704
	s_waitcnt lgkmcnt(0)
	ds_read2_b32 v[6:7], v17 offset1:8
	ds_read2_b32 v[30:31], v17 offset0:33 offset1:41
	ds_read2_b32 v[32:33], v17 offset0:66 offset1:74
	ds_read2_b32 v[34:35], v17 offset0:99 offset1:107
	ds_read2_b32 v[36:37], v17 offset0:132 offset1:140
	ds_read2_b32 v[38:39], v17 offset0:165 offset1:173
	s_waitcnt lgkmcnt(5)
	v_bfe_u32 v2, v6, 16, 1
	v_add3_u32 v2, v6, v2, s17
	s_waitcnt lgkmcnt(4)
	v_bfe_u32 v3, v30, 16, 1
	v_lshrrev_b32_e32 v2, 16, v2
	v_add3_u32 v3, v30, v3, s17
	v_and_or_b32 v2, v3, s18, v2
	s_waitcnt lgkmcnt(3)
	v_bfe_u32 v3, v32, 16, 1
	v_add3_u32 v3, v32, v3, s17
	s_waitcnt lgkmcnt(2)
	v_bfe_u32 v4, v34, 16, 1
	ds_read2_b32 v[40:41], v17 offset0:198 offset1:206
	v_lshrrev_b32_e32 v3, 16, v3
	v_add3_u32 v4, v34, v4, s17
	ds_read2_b32 v[42:43], v17 offset0:231 offset1:239
	v_and_or_b32 v3, v4, s18, v3
	s_waitcnt lgkmcnt(3)
	v_bfe_u32 v4, v36, 16, 1
	v_add3_u32 v4, v36, v4, s17
	s_waitcnt lgkmcnt(2)
	v_bfe_u32 v5, v38, 16, 1
	v_lshrrev_b32_e32 v4, 16, v4
	v_add3_u32 v5, v38, v5, s17
	v_and_or_b32 v4, v5, s18, v4
	s_waitcnt lgkmcnt(1)
	v_bfe_u32 v5, v40, 16, 1
	v_or_b32_e32 v44, s12, v74
	s_ashr_i32 s15, s14, 31
	v_add3_u32 v5, v40, v5, s17
	s_waitcnt lgkmcnt(0)
	v_bfe_u32 v6, v42, 16, 1
	v_ashrrev_i32_e32 v45, 31, v44
	v_lshl_add_u64 v[8:9], s[14:15], 1, v[28:29]
	v_lshrrev_b32_e32 v5, 16, v5
	v_add3_u32 v6, v42, v6, s17
	v_lshlrev_b64 v[44:45], 11, v[44:45]
	v_and_or_b32 v5, v6, s18, v5
	v_lshl_add_u64 v[44:45], v[8:9], 0, v[44:45]
	global_store_dwordx4 v[44:45], v[2:5], off nt
	v_bfe_u32 v6, v43, 16, 1
	v_add3_u32 v6, v43, v6, s17
	v_bfe_u32 v2, v7, 16, 1
	v_add3_u32 v2, v7, v2, s17
	v_bfe_u32 v3, v31, 16, 1
	v_lshrrev_b32_e32 v2, 16, v2
	v_add3_u32 v3, v31, v3, s17
	v_and_or_b32 v2, v3, s18, v2
	v_bfe_u32 v3, v33, 16, 1
	v_add3_u32 v3, v33, v3, s17
	v_bfe_u32 v4, v35, 16, 1
	v_lshrrev_b32_e32 v3, 16, v3
	v_add3_u32 v4, v35, v4, s17
	v_and_or_b32 v3, v4, s18, v3
	v_bfe_u32 v4, v37, 16, 1
	v_add3_u32 v4, v37, v4, s17
	v_bfe_u32 v5, v39, 16, 1
	v_lshrrev_b32_e32 v4, 16, v4
	v_add3_u32 v5, v39, v5, s17
	v_and_or_b32 v4, v5, s18, v4
	v_bfe_u32 v5, v41, 16, 1
	v_add3_u32 v5, v41, v5, s17
	v_lshrrev_b32_e32 v5, 16, v5
	v_and_or_b32 v5, v6, s18, v5
	v_or_b32_e32 v6, s12, v76
	v_ashrrev_i32_e32 v7, 31, v6
	v_lshlrev_b64 v[6:7], 11, v[6:7]
	ds_read2_b32 v[30:31], v17 offset0:16 offset1:24
	v_lshl_add_u64 v[6:7], v[8:9], 0, v[6:7]
	global_store_dwordx4 v[6:7], v[2:5], off nt
	ds_read2_b32 v[6:7], v17 offset0:49 offset1:57
	ds_read2_b32 v[32:33], v17 offset0:82 offset1:90
	ds_read2_b32 v[34:35], v17 offset0:115 offset1:123
	s_waitcnt lgkmcnt(3)
	v_bfe_u32 v2, v30, 16, 1
	v_add3_u32 v2, v30, v2, s17
	s_waitcnt lgkmcnt(2)
	v_bfe_u32 v3, v6, 16, 1
	ds_read2_b32 v[36:37], v17 offset0:148 offset1:156
	v_lshrrev_b32_e32 v2, 16, v2
	v_add3_u32 v3, v6, v3, s17
	ds_read2_b32 v[38:39], v17 offset0:181 offset1:189
	v_and_or_b32 v2, v3, s18, v2
	s_waitcnt lgkmcnt(3)
	v_bfe_u32 v3, v32, 16, 1
	v_add3_u32 v3, v32, v3, s17
	s_waitcnt lgkmcnt(2)
	v_bfe_u32 v4, v34, 16, 1
	ds_read2_b32 v[40:41], v17 offset0:214 offset1:222
	v_lshrrev_b32_e32 v3, 16, v3
	v_add3_u32 v4, v34, v4, s17
	ds_read2_b32 v[42:43], v17 offset0:247 offset1:255
	v_and_or_b32 v3, v4, s18, v3
	s_waitcnt lgkmcnt(3)
	v_bfe_u32 v4, v36, 16, 1
	v_add3_u32 v4, v36, v4, s17
	s_waitcnt lgkmcnt(2)
	v_bfe_u32 v5, v38, 16, 1
	v_lshrrev_b32_e32 v4, 16, v4
	v_add3_u32 v5, v38, v5, s17
	v_and_or_b32 v4, v5, s18, v4
	s_waitcnt lgkmcnt(1)
	v_bfe_u32 v5, v40, 16, 1
	v_or_b32_e32 v44, s12, v77
	v_add3_u32 v5, v40, v5, s17
	s_waitcnt lgkmcnt(0)
	v_bfe_u32 v6, v42, 16, 1
	v_ashrrev_i32_e32 v45, 31, v44
	v_lshrrev_b32_e32 v5, 16, v5
	v_add3_u32 v6, v42, v6, s17
	v_lshlrev_b64 v[44:45], 11, v[44:45]
	v_and_or_b32 v5, v6, s18, v5
	v_lshl_add_u64 v[44:45], v[8:9], 0, v[44:45]
	global_store_dwordx4 v[44:45], v[2:5], off nt
	v_bfe_u32 v6, v43, 16, 1
	v_add3_u32 v6, v43, v6, s17
	v_bfe_u32 v2, v31, 16, 1
	v_add3_u32 v2, v31, v2, s17
	v_bfe_u32 v3, v7, 16, 1
	v_lshrrev_b32_e32 v2, 16, v2
	v_add3_u32 v3, v7, v3, s17
	v_and_or_b32 v2, v3, s18, v2
	v_bfe_u32 v3, v33, 16, 1
	v_add3_u32 v3, v33, v3, s17
	v_bfe_u32 v4, v35, 16, 1
	v_lshrrev_b32_e32 v3, 16, v3
	v_add3_u32 v4, v35, v4, s17
	v_and_or_b32 v3, v4, s18, v3
	v_bfe_u32 v4, v37, 16, 1
	v_add3_u32 v4, v37, v4, s17
	v_bfe_u32 v5, v39, 16, 1
	v_lshrrev_b32_e32 v4, 16, v4
	v_add3_u32 v5, v39, v5, s17
	v_and_or_b32 v4, v5, s18, v4
	v_bfe_u32 v5, v41, 16, 1
	v_add3_u32 v5, v41, v5, s17
	v_lshrrev_b32_e32 v5, 16, v5
	v_and_or_b32 v5, v6, s18, v5
	v_or_b32_e32 v6, s12, v78
	v_ashrrev_i32_e32 v7, 31, v6
	v_lshlrev_b64 v[6:7], 11, v[6:7]
	v_lshl_add_u64 v[6:7], v[8:9], 0, v[6:7]
	global_store_dwordx4 v[6:7], v[2:5], off nt
	s_waitcnt lgkmcnt(0)
	s_branch .LBB0_679

.LBB0_870:
	s_or_b64 exec, exec, s[6:7]
	s_waitcnt lgkmcnt(0)
	s_barrier
	ds_read_b32 v2, v165
	s_mov_b64 s[6:7], -1
	s_waitcnt lgkmcnt(0)
	v_cmp_lt_i32_e32 vcc, s12, v2
	v_readfirstlane_b32 s10, v2
	s_cbranch_vccnz .LBB0_865
	s_lshl_b32 s6, s10, 7
	s_ashr_i32 s7, s6, 31
	s_lshl_b64 s[6:7], s[6:7], 10
	v_lshl_add_u64 v[58:59], v[132:133], 0, s[6:7]
	s_waitcnt vmcnt(0)
	v_add_co_u32_e32 v10, vcc, 0x2000, v58
	s_ashr_i32 s11, s10, 31
	s_nop 0
	v_addc_co_u32_e32 v11, vcc, 0, v59, vcc
	global_load_dwordx4 v[2:5], v[58:59], off nt
	global_load_dwordx4 v[6:9], v[10:11], off nt
	v_add_co_u32_e32 v10, vcc, 0x4000, v58
	s_lshl_b64 s[6:7], s[10:11], 16
	s_nop 0
	v_addc_co_u32_e32 v11, vcc, 0, v59, vcc
	v_add_co_u32_e32 v14, vcc, 0x6000, v58
	s_lshl_b64 s[8:9], s[10:11], 17
	s_nop 0
	v_addc_co_u32_e32 v15, vcc, 0, v59, vcc
	v_add_co_u32_e32 v18, vcc, 0x8000, v58
	global_load_dwordx4 v[10:13], v[10:11], off nt
	s_nop 0
	global_load_dwordx4 v[14:17], v[14:15], off nt
	v_addc_co_u32_e32 v19, vcc, 0, v59, vcc
	v_add_co_u32_e32 v22, vcc, 0xa000, v58
	s_lshl_b64 s[10:11], s[10:11], 18
	s_nop 0
	v_addc_co_u32_e32 v23, vcc, 0, v59, vcc
	v_add_co_u32_e32 v26, vcc, 0xc000, v58
	global_load_dwordx4 v[18:21], v[18:19], off nt
	s_nop 0
	global_load_dwordx4 v[22:25], v[22:23], off nt
	v_addc_co_u32_e32 v27, vcc, 0, v59, vcc
	v_add_co_u32_e32 v30, vcc, 0xe000, v58
	s_mov_b32 s14, 0
	s_nop 0
	v_addc_co_u32_e32 v31, vcc, 0, v59, vcc
	v_add_co_u32_e32 v34, vcc, 0x10000, v58
	global_load_dwordx4 v[26:29], v[26:27], off nt
	s_nop 0
	global_load_dwordx4 v[30:33], v[30:31], off nt
	v_addc_co_u32_e32 v35, vcc, 0, v59, vcc
	v_add_co_u32_e32 v38, vcc, 0x12000, v58
	v_lshl_add_u64 v[148:149], v[146:147], 0, s[10:11]
	s_nop 0
	v_addc_co_u32_e32 v39, vcc, 0, v59, vcc
	v_add_co_u32_e32 v42, vcc, 0x14000, v58
	global_load_dwordx4 v[34:37], v[34:35], off nt
	s_nop 0
	global_load_dwordx4 v[38:41], v[38:39], off nt
	v_addc_co_u32_e32 v43, vcc, 0, v59, vcc
	v_add_co_u32_e32 v46, vcc, 0x16000, v58
	s_mov_b64 s[10:11], -1
	s_nop 0
	v_addc_co_u32_e32 v47, vcc, 0, v59, vcc
	v_add_co_u32_e32 v50, vcc, 0x18000, v58
	global_load_dwordx4 v[42:45], v[42:43], off nt
	s_nop 0
	global_load_dwordx4 v[46:49], v[46:47], off nt
	v_addc_co_u32_e32 v51, vcc, 0, v59, vcc
	v_add_co_u32_e32 v54, vcc, 0x1a000, v58
	s_nop 1
	v_addc_co_u32_e32 v55, vcc, 0, v59, vcc
	v_add_co_u32_e32 v60, vcc, 0x1c000, v58
	global_load_dwordx4 v[50:53], v[50:51], off nt
	s_nop 0
	global_load_dwordx4 v[54:57], v[54:55], off nt
	v_addc_co_u32_e32 v61, vcc, 0, v59, vcc
	v_add_co_u32_e32 v62, vcc, 0x1e000, v58
	s_nop 1
	v_addc_co_u32_e32 v63, vcc, 0, v59, vcc
	global_load_dwordx4 v[58:61], v[60:61], off nt
	s_nop 0
	global_load_dwordx4 v[62:65], v[62:63], off nt
	s_waitcnt vmcnt(15)
	ds_write_b16 v135, v2
	ds_write_b16_d16_hi v135, v2 offset:272
	ds_write_b16 v135, v3 offset:544
	ds_write_b16_d16_hi v135, v3 offset:816
	ds_write_b16 v135, v4 offset:1088
	ds_write_b16_d16_hi v135, v4 offset:1360
	ds_write_b16 v135, v5 offset:1632
	ds_write_b16_d16_hi v135, v5 offset:1904
	s_waitcnt vmcnt(14)
	ds_write_b16 v135, v6 offset:16
	ds_write_b16_d16_hi v135, v6 offset:256
	ds_write_b16 v135, v7 offset:560
	ds_write_b16_d16_hi v135, v7 offset:800
	ds_write_b16 v135, v8 offset:1104
	ds_write_b16_d16_hi v135, v8 offset:1344
	ds_write_b16 v135, v9 offset:1648
	ds_write_b16_d16_hi v135, v9 offset:1888
	s_waitcnt vmcnt(13)
	ds_write_b16 v135, v10 offset:32
	ds_write_b16_d16_hi v135, v10 offset:304
	ds_write_b16 v135, v11 offset:512
	ds_write_b16_d16_hi v135, v11 offset:784
	ds_write_b16 v135, v12 offset:1120
	ds_write_b16_d16_hi v135, v12 offset:1392
	ds_write_b16 v135, v13 offset:1600
	ds_write_b16_d16_hi v135, v13 offset:1872
	s_waitcnt vmcnt(12)
	ds_write_b16 v135, v14 offset:48
	ds_write_b16_d16_hi v135, v14 offset:288
	ds_write_b16 v135, v15 offset:528
	ds_write_b16_d16_hi v135, v15 offset:768
	ds_write_b16 v135, v16 offset:1136
	ds_write_b16_d16_hi v135, v16 offset:1376
	ds_write_b16 v135, v17 offset:1616
	ds_write_b16_d16_hi v135, v17 offset:1856
	s_waitcnt vmcnt(11)
	ds_write_b16 v135, v18 offset:64
	ds_write_b16_d16_hi v135, v18 offset:336
	ds_write_b16 v135, v19 offset:608
	ds_write_b16_d16_hi v135, v19 offset:880
	ds_write_b16 v135, v20 offset:1024
	ds_write_b16_d16_hi v135, v20 offset:1296
	ds_write_b16 v135, v21 offset:1568
	ds_write_b16_d16_hi v135, v21 offset:1840
	s_waitcnt vmcnt(10)
	ds_write_b16 v135, v22 offset:80
	ds_write_b16_d16_hi v135, v22 offset:320
	ds_write_b16 v135, v23 offset:624
	ds_write_b16_d16_hi v135, v23 offset:864
	ds_write_b16 v135, v24 offset:1040
	ds_write_b16_d16_hi v135, v24 offset:1280
	ds_write_b16 v135, v25 offset:1584
	ds_write_b16_d16_hi v135, v25 offset:1824
	s_waitcnt vmcnt(9)
	ds_write_b16 v135, v26 offset:96
	ds_write_b16_d16_hi v135, v26 offset:368
	ds_write_b16 v135, v27 offset:576
	ds_write_b16_d16_hi v135, v27 offset:848
	ds_write_b16 v135, v28 offset:1056
	ds_write_b16_d16_hi v135, v28 offset:1328
	ds_write_b16 v135, v29 offset:1536
	ds_write_b16_d16_hi v135, v29 offset:1808
	s_waitcnt vmcnt(8)
	ds_write_b16 v135, v30 offset:112
	ds_write_b16_d16_hi v135, v30 offset:352
	ds_write_b16 v135, v31 offset:592
	ds_write_b16_d16_hi v135, v31 offset:832
	ds_write_b16 v135, v32 offset:1072
	ds_write_b16_d16_hi v135, v32 offset:1312
	ds_write_b16 v135, v33 offset:1552
	ds_write_b16_d16_hi v135, v33 offset:1792
	s_waitcnt vmcnt(7)
	ds_write_b16 v162, v34 offset:128
	ds_write_b16_d16_hi v162, v34 offset:400
	ds_write_b16 v162, v35 offset:672
	ds_write_b16_d16_hi v162, v35 offset:944
	ds_write_b16 v162, v36 offset:1216
	ds_write_b16_d16_hi v162, v36 offset:1488
	ds_write_b16 v162, v37 offset:1760
	ds_write_b16_d16_hi v162, v37 offset:2032
	s_waitcnt vmcnt(6)
	ds_write_b16 v162, v38 offset:144
	ds_write_b16_d16_hi v162, v38 offset:384
	ds_write_b16 v162, v39 offset:688
	ds_write_b16_d16_hi v162, v39 offset:928
	ds_write_b16 v162, v40 offset:1232
	ds_write_b16_d16_hi v162, v40 offset:1472
	ds_write_b16 v162, v41 offset:1776
	ds_write_b16_d16_hi v162, v41 offset:2016
	s_waitcnt vmcnt(5)
	ds_write_b16 v162, v42 offset:160
	ds_write_b16_d16_hi v162, v42 offset:432
	ds_write_b16 v162, v43 offset:640
	ds_write_b16_d16_hi v162, v43 offset:912
	ds_write_b16 v162, v44 offset:1248
	ds_write_b16_d16_hi v162, v44 offset:1520
	ds_write_b16 v162, v45 offset:1728
	ds_write_b16_d16_hi v162, v45 offset:2000
	s_waitcnt vmcnt(4)
	ds_write_b16 v162, v46 offset:176
	ds_write_b16_d16_hi v162, v46 offset:416
	ds_write_b16 v162, v47 offset:656
	ds_write_b16_d16_hi v162, v47 offset:896
	ds_write_b16 v162, v48 offset:1264
	ds_write_b16_d16_hi v162, v48 offset:1504
	ds_write_b16 v162, v49 offset:1744
	ds_write_b16_d16_hi v162, v49 offset:1984
	s_waitcnt vmcnt(3)
	ds_write_b16 v162, v50 offset:192
	ds_write_b16_d16_hi v162, v50 offset:464
	ds_write_b16 v162, v51 offset:736
	ds_write_b16_d16_hi v162, v51 offset:1008
	ds_write_b16 v162, v52 offset:1152
	ds_write_b16_d16_hi v162, v52 offset:1424
	ds_write_b16 v162, v53 offset:1696
	ds_write_b16_d16_hi v162, v53 offset:1968
	s_waitcnt vmcnt(2)
	ds_write_b16 v162, v54 offset:208
	ds_write_b16_d16_hi v162, v54 offset:448
	ds_write_b16 v162, v55 offset:752
	ds_write_b16_d16_hi v162, v55 offset:992
	ds_write_b16 v162, v56 offset:1168
	ds_write_b16_d16_hi v162, v56 offset:1408
	ds_write_b16 v162, v57 offset:1712
	ds_write_b16_d16_hi v162, v57 offset:1952
	s_waitcnt vmcnt(1)
	ds_write_b16 v162, v58 offset:224
	ds_write_b16_d16_hi v162, v58 offset:496
	ds_write_b16 v162, v59 offset:704
	ds_write_b16_d16_hi v162, v59 offset:976
	ds_write_b16 v162, v60 offset:1184
	ds_write_b16_d16_hi v162, v60 offset:1456
	ds_write_b16 v162, v61 offset:1664
	ds_write_b16_d16_hi v162, v61 offset:1936
	s_waitcnt vmcnt(0)
	ds_write_b16 v162, v62 offset:240
	ds_write_b16_d16_hi v162, v62 offset:480
	ds_write_b16 v162, v63 offset:720
	ds_write_b16_d16_hi v162, v63 offset:960
	ds_write_b16 v162, v64 offset:1200
	ds_write_b16_d16_hi v162, v64 offset:1440
	ds_write_b16 v162, v65 offset:1680
	ds_write_b16_d16_hi v162, v65 offset:1920
	s_waitcnt lgkmcnt(0)
	ds_read_b128 v[2:5], v166
	ds_read_b128 v[6:9], v166 offset:4096
	ds_read_b128 v[10:13], v166 offset:8192
	ds_read_b128 v[14:17], v166 offset:12288
	ds_read_b128 v[18:21], v167
	ds_read_b128 v[22:25], v167 offset:4096
	ds_read_b128 v[26:29], v167 offset:8192
	ds_read_b128 v[30:33], v167 offset:12288
	ds_read_b128 v[34:37], v168
	ds_read_b128 v[38:41], v168 offset:4096
	ds_read_b128 v[42:45], v168 offset:8192
	ds_read_b128 v[46:49], v168 offset:12288
	ds_read_b128 v[50:53], v169
	ds_read_b128 v[54:57], v169 offset:4096
	ds_read_b128 v[58:61], v169 offset:8192
	ds_read_b128 v[62:65], v169 offset:12288
